# baseline (speedup 1.0000x reference)
; __device__ __forceinline__ float lo2f(unsigned u) { return __uint_as_float(u << 16); }
; __device__ __forceinline__ float hi2f(unsigned u) { return __uint_as_float(u & 0xffff0000u); }
; template <int LSEL>
; __device__ __forceinline__ void hy_apply(const HyRaw& rw, float w0, float w1, float w2, float bias, bf16_t* dst, int toZ) {
;     ...
;     x[1] = lo2f(u.x); x[2] = hi2f(u.x); x[3] = lo2f(u.y); x[4] = hi2f(u.y);
;     x[5] = lo2f(u.z); x[6] = hi2f(u.z); x[7] = lo2f(u.w); x[8] = hi2f(u.w);
;     float o[8];
; #pragma unroll
;     for (int j = 0; j < 8; ++j) o[j] = w0 * x[j] + w1 * x[j + 1] + w2 * x[j + 2] + bias;
;     uint4 ou;
;     ou.x = pack2(o[0], o[1]); ou.y = pack2(o[2], o[3]); ou.z = pack2(o[4], o[5]); ou.w = pack2(o[6], o[7]);
;     *(uint4*)(dst + (toZ ? b * RS + PADF + s : b * HyC<LSEL>::XS + s)) = ou;
; template <int LSEL>
; __device__ __forceinline__ void hy_conv(const bf16_t* Z, const bf16_t* G, f32x4 (&acc)[4][4], int w, int lane) {
;     ...
;   const int r = lane & 15, quad = lane >> 4;
;   const int zb = (LSEL ? (r & 7) * RS + (r >> 3) * 64 : r * RS) + PADF + quad * 8;
;   const int s = (8 - (r & 7)) & 7;
;   const bool t2 = (s & 4) != 0, t1 = (s & 2) != 0;
;   const unsigned sh = (s & 1) * 16;
;   const int q0 = w * 4;
;   const int i_lo = q0 * BPT, i_hi = (q0 + 4) * BPT - 1;
;   for (int d = i_lo - (NB - 1); d <= i_hi; ++d) {
;     bf16x8 bf[4][2];
; #pragma unroll
;     for (int k = 0; k < 4; ++k) {
;       int js = (q0 + k) * BPT - d;
;       js = min(max(js, LSEL ? -1 : 0), NB - 1);
;       const bf16_t* bp = Z + zb + 64 * js;
;       bf[k][0] = *(const bf16x8*)bp;
;       bf[k][1] = *(const bf16x8*)(bp + 32);
;     }
;     const bf16_t* gb = G + (L - 64 * d + 8 * quad - r - s);
;     bf16x8 F[6];
; #pragma unroll
;     for (int u = 0; u < 6; ++u) F[u] = hy_afrag(gb + 16 * (u - 3), t2, t1, sh);
.LBB0_833:
	s_or_b64 exec, exec, s[6:7]
	v_add_u32_e32 v41, 0x7000, v74
	v_ashrrev_i32_e32 v42, 31, v41
	v_lshrrev_b32_e32 v42, 21, v42
	v_add_u32_e32 v42, v41, v42
	v_and_b32_e32 v54, 0xfffff800, v42
	v_cmp_ne_u32_e64 s[4:5], v41, v54
	v_ashrrev_i32_e32 v53, 11, v42
	v_and_b32_e32 v44, 0xffff0000, v36
	v_cndmask_b32_e64 v42, 0, v0, s[4:5]
	v_lshlrev_b32_e32 v0, 16, v36
	v_lshlrev_b32_e32 v45, 16, v37
	v_pk_mov_b32 v[36:37], v[36:37], v[38:39] op_sel:[1,0]
	v_sub_u32_e32 v43, v41, v54
	v_and_b32_e32 v37, 16, v37
	v_and_b32_e32 v36, 0xffff0000, v36
	s_movk_i32 s4, 0x7f8
	v_and_b32_e32 v47, 16, v39
	v_and_b32_e32 v46, 0xffff0000, v38
	v_lshlrev_b32_e32 v49, 16, v39
	v_and_b32_e32 v51, 0xffff0000, v39
	v_lshlrev_b32_e32 v39, 16, v38
	v_mov_b32_e32 v38, v36
	v_pk_mov_b32 v[36:37], v[44:45], v[36:37] op_sel:[1,0]
	v_cmp_gt_i32_e64 s[4:5], s4, v43
	v_mov_b32_e32 v43, v44
	v_pk_mul_f32 v[36:37], v[72:73], v[36:37]
	v_pk_mul_f32 v[42:43], v[66:67], v[42:43]
	v_pk_fma_f32 v[36:37], v[64:65], v[44:45], v[36:37]
	v_pk_fma_f32 v[42:43], v[70:71], v[0:1], v[42:43] op_sel_hi:[1,0,1]
	v_pk_fma_f32 v[36:37], v[68:69], v[38:39], v[36:37]
	v_pk_fma_f32 v[42:43], v[68:69], v[44:45], v[42:43]
	v_pk_add_f32 v[44:45], v[2:3], v[36:37]
	v_pk_mov_b32 v[36:37], v[38:39], v[46:47] op_sel:[1,0]
	v_mov_b32_e32 v48, v46
	v_pk_mul_f32 v[36:37], v[72:73], v[36:37]
	v_mov_b32_e32 v50, v49
	v_pk_fma_f32 v[36:37], v[64:65], v[38:39], v[36:37]
	v_cndmask_b32_e64 v41, 0, v40, s[4:5]
	v_pk_fma_f32 v[36:37], v[68:69], v[48:49], v[36:37]
	v_mov_b32_e32 v40, v51
	v_pk_add_f32 v[38:39], v[2:3], v[36:37]
	v_pk_mul_f32 v[36:37], v[72:73], v[50:51]
	v_pk_add_f32 v[42:43], v[2:3], v[42:43]
	v_pk_fma_f32 v[36:37], v[64:65], v[48:49], v[36:37]
	v_cvt_pk_bf16_f32 v38, v38, v39
	v_pk_fma_f32 v[36:37], v[68:69], v[40:41], v[36:37]
	v_sub_u32_e32 v0, v74, v54
	v_pk_add_f32 v[2:3], v[2:3], v[36:37]
	v_and_b32_e32 v52, 63, v150
	v_cvt_pk_bf16_f32 v39, v2, v3
	v_mul_i32_i24_e32 v2, 0x1010, v53
	v_cvt_pk_bf16_f32 v36, v42, v43
	v_cvt_pk_bf16_f32 v37, v44, v45
	v_lshl_add_u32 v0, v0, 1, v2
	ds_write_b128 v0, v[36:39] offset:57344
	v_sub_u32_e32 v0, 0, v52
	v_and_b32_e32 v2, 4, v0
	v_cmp_eq_u32_e64 s[4:5], 0, v2
	v_and_b32_e32 v2, 2, v0
	v_lshlrev_b32_e32 v152, 4, v0
	v_and_b32_e32 v0, 7, v0
	v_and_b32_e32 v165, 15, v150
	v_ashrrev_i32_e32 v164, 6, v150
	v_cmp_eq_u32_e64 s[6:7], 0, v2
	v_and_b32_e32 v2, 48, v150
	s_movk_i32 s10, 0x1010
	v_add_lshl_u32 v0, v0, v165, 1
	v_mad_u32_u24 v153, v165, s10, v2
	v_sub_u32_e32 v0, v2, v0
	v_lshlrev_b32_e32 v2, 9, v164
	v_sub_u32_e32 v155, v0, v2
	v_mov_b32_e32 v2, v1
	v_mov_b32_e32 v3, v1
	v_mov_b32_e32 v0, v1
	v_mov_b64_e32 v[38:39], v[2:3]
	v_mov_b64_e32 v[42:43], v[2:3]
	v_mov_b64_e32 v[46:47], v[2:3]
	v_mov_b64_e32 v[50:51], v[2:3]
	v_mov_b64_e32 v[54:55], v[2:3]
	v_mov_b64_e32 v[58:59], v[2:3]
	v_mov_b64_e32 v[62:63], v[2:3]
	v_mov_b64_e32 v[66:67], v[2:3]
	v_mov_b64_e32 v[70:71], v[2:3]
	v_mov_b64_e32 v[74:75], v[2:3]
	v_mov_b64_e32 v[78:79], v[2:3]
	v_mov_b64_e32 v[82:83], v[2:3]
	v_mov_b64_e32 v[86:87], v[2:3]
	v_mov_b64_e32 v[90:91], v[2:3]
	v_mov_b64_e32 v[94:95], v[2:3]
	v_mov_b64_e32 v[98:99], v[2:3]
	s_mov_b32 s8, 31
	s_mov_b32 s9, 0
	v_add_u32_e32 v154, 0xf80, v153
	v_mov_b64_e32 v[36:37], v[0:1]
	v_mov_b64_e32 v[40:41], v[0:1]
	v_mov_b64_e32 v[44:45], v[0:1]
	v_mov_b64_e32 v[48:49], v[0:1]
	v_mov_b64_e32 v[52:53], v[0:1]
	v_mov_b64_e32 v[56:57], v[0:1]
	v_mov_b64_e32 v[60:61], v[0:1]
	v_mov_b64_e32 v[64:65], v[0:1]
	v_mov_b64_e32 v[68:69], v[0:1]
	v_mov_b64_e32 v[72:73], v[0:1]
	v_mov_b64_e32 v[76:77], v[0:1]
	v_mov_b64_e32 v[80:81], v[0:1]
	v_mov_b64_e32 v[84:85], v[0:1]
	v_mov_b64_e32 v[88:89], v[0:1]
	v_mov_b64_e32 v[92:93], v[0:1]
	v_mov_b64_e32 v[96:97], v[0:1]
	v_lshrrev_b32_e32 v176, 3, v152
	v_and_b32_e32 v176, 12, v176
	v_add_u32_e32 v176, v176, v155
	v_add_u32_e32 v176, 0x228a0, v176
	s_waitcnt lgkmcnt(0)
	s_barrier
	ds_read2_b32 v[108:109], v176 offset0:32 offset1:33
	ds_read2_b32 v[110:111], v176 offset0:34 offset1:35
	ds_read_b32 v2, v176 offset:144
	ds_read2_b32 v[120:121], v176 offset0:40 offset1:41
	ds_read2_b32 v[122:123], v176 offset0:42 offset1:43
	ds_read_b32 v3, v176 offset:176
	s_waitcnt lgkmcnt(0)
	v_alignbit_b32 v140, v109, v108, v152
	v_alignbit_b32 v141, v110, v109, v152
	v_alignbit_b32 v142, v111, v110, v152
	v_alignbit_b32 v143, v2, v111, v152
	v_alignbit_b32 v144, v121, v120, v152
	v_alignbit_b32 v145, v122, v121, v152
	v_alignbit_b32 v146, v123, v122, v152
	v_alignbit_b32 v147, v3, v123, v152
	s_branch .LBB0_835
; template <int LSEL>
; __device__ __forceinline__ void hy_conv(const bf16_t* Z, const bf16_t* G, f32x4 (&acc)[4][4], int w, int lane) {
;     ...
;   for (int d = i_lo - (NB - 1); d <= i_hi; ++d) {
;     bf16x8 bf[4][2];
; #pragma unroll
;     for (int k = 0; k < 4; ++k) {
;       int js = (q0 + k) * BPT - d;
;       js = min(max(js, LSEL ? -1 : 0), NB - 1);
;       const bf16_t* bp = Z + zb + 64 * js;
;       bf[k][0] = *(const bf16x8*)bp;
;       bf[k][1] = *(const bf16x8*)(bp + 32);
;     }
;     const bf16_t* gb = G + (L - 64 * d + 8 * quad - r - s);
;     bf16x8 F[6];
; #pragma unroll
;     for (int u = 0; u < 6; ++u) F[u] = hy_afrag(gb + 16 * (u - 3), t2, t1, sh);
; #pragma unroll
;     for (int k = 0; k < 4; ++k) {
;       const int js = (q0 + k) * BPT - d;
;       const bool valid = LSEL ? (js >= -1 && js <= NB - 1) : (js >= 0 && js <= NB - 1);
;       if (valid) {
; #pragma unroll
;         for (int mt = 0; mt < 4; ++mt) {
;           acc[k][mt] = __builtin_amdgcn_mfma_f32_16x16x32_bf16(F[3 - mt], bf[k][0], acc[k][mt], 0, 0, 0);
;           acc[k][mt] = __builtin_amdgcn_mfma_f32_16x16x32_bf16(F[5 - mt], bf[k][1], acc[k][mt], 0, 0, 0);
;         }
;       }
;     }
.LBB0_834:
	s_addk_i32 s9, 0xff80
	s_add_i32 s8, s8, -1
	s_cmpk_lg_i32 s9, 0xee80
	s_cbranch_scc0 .LBB0_843
	s_branch .Lhyb_b835
.LBB0_835:
	v_add_u32_e32 v0, s9, v176
	ds_read2_b32 v[108:109], v0 offset1:1
	ds_read2_b32 v[110:111], v0 offset0:2 offset1:3
	ds_read_b32 v2, v0 offset:16
	ds_read2_b32 v[120:121], v0 offset0:8 offset1:9
	ds_read2_b32 v[122:123], v0 offset0:10 offset1:11
	ds_read_b32 v3, v0 offset:48
	ds_read2_b32 v[124:125], v0 offset0:16 offset1:17
	ds_read2_b32 v[126:127], v0 offset0:18 offset1:19
	ds_read_b32 v177, v0 offset:80
	ds_read2_b32 v[136:137], v0 offset0:24 offset1:25
	ds_read2_b32 v[138:139], v0 offset0:26 offset1:27
	ds_read_b32 v178, v0 offset:112
	s_add_i32 s12, s8, 1
	v_med3_i32 v0, s12, 0, 31
	v_lshl_add_u32 v0, v0, 7, v153
	s_add_i32 s11, s8, 2
	ds_read_b128 v[128:131], v0
	ds_read_b128 v[132:135], v0 offset:64
	s_waitcnt lgkmcnt(11)
	v_alignbit_b32 v108, v109, v108, v152
	v_alignbit_b32 v109, v110, v109, v152
	v_alignbit_b32 v110, v111, v110, v152
	v_alignbit_b32 v111, v2, v111, v152
	v_med3_i32 v0, s11, 0, 31
	s_add_i32 s10, s8, 3
	v_lshl_add_u32 v0, v0, 7, v153
	s_min_u32 s13, s10, 31
	ds_read_b128 v[112:115], v0
	ds_read_b128 v[116:119], v0 offset:64
	s_waitcnt lgkmcnt(10)
	v_alignbit_b32 v120, v121, v120, v152
	v_alignbit_b32 v121, v122, v121, v152
	v_alignbit_b32 v122, v123, v122, v152
	v_alignbit_b32 v123, v3, v123, v152
	v_lshl_add_u32 v0, s13, 7, v153
	ds_read_b128 v[100:103], v0
	ds_read_b128 v[104:107], v0 offset:64
	s_waitcnt lgkmcnt(9)
	v_alignbit_b32 v124, v125, v124, v152
	v_alignbit_b32 v125, v126, v125, v152
	v_alignbit_b32 v126, v127, v126, v152
	v_alignbit_b32 v127, v177, v127, v152
	s_waitcnt lgkmcnt(6)
	v_alignbit_b32 v136, v137, v136, v152
	v_alignbit_b32 v137, v138, v137, v152
	v_alignbit_b32 v138, v139, v138, v152
	v_alignbit_b32 v139, v178, v139, v152
	s_waitcnt lgkmcnt(0)
	s_cmp_lt_u32 s8, 29
	s_cbranch_scc0 .Lhy_slow_835
	v_add_u32_e32 v0, s9, v154
	ds_read_b128 v[166:169], v0
	ds_read_b128 v[170:173], v0 offset:64
	v_mfma_f32_16x16x32_bf16 v[64:67], v[136:139], v[112:115], v[64:67]
	v_mfma_f32_16x16x32_bf16 v[60:63], v[124:127], v[112:115], v[60:63]
	v_mfma_f32_16x16x32_bf16 v[56:59], v[120:123], v[112:115], v[56:59]
	v_mfma_f32_16x16x32_bf16 v[52:55], v[108:111], v[112:115], v[52:55]
	v_mfma_f32_16x16x32_bf16 v[64:67], v[144:147], v[116:119], v[64:67]
	v_mfma_f32_16x16x32_bf16 v[60:63], v[140:143], v[116:119], v[60:63]
	v_mfma_f32_16x16x32_bf16 v[56:59], v[136:139], v[116:119], v[56:59]
	v_mfma_f32_16x16x32_bf16 v[52:55], v[124:127], v[116:119], v[52:55]
	v_mfma_f32_16x16x32_bf16 v[80:83], v[136:139], v[128:131], v[80:83]
	v_mfma_f32_16x16x32_bf16 v[76:79], v[124:127], v[128:131], v[76:79]
	v_mfma_f32_16x16x32_bf16 v[72:75], v[120:123], v[128:131], v[72:75]
	v_mfma_f32_16x16x32_bf16 v[68:71], v[108:111], v[128:131], v[68:71]
	v_mfma_f32_16x16x32_bf16 v[80:83], v[144:147], v[132:135], v[80:83]
	v_mfma_f32_16x16x32_bf16 v[76:79], v[140:143], v[132:135], v[76:79]
	v_mfma_f32_16x16x32_bf16 v[72:75], v[136:139], v[132:135], v[72:75]
	v_mfma_f32_16x16x32_bf16 v[68:71], v[124:127], v[132:135], v[68:71]
	v_mfma_f32_16x16x32_bf16 v[48:51], v[136:139], v[100:103], v[48:51]
	v_mfma_f32_16x16x32_bf16 v[44:47], v[124:127], v[100:103], v[44:47]
	v_mfma_f32_16x16x32_bf16 v[40:43], v[120:123], v[100:103], v[40:43]
	v_mfma_f32_16x16x32_bf16 v[36:39], v[108:111], v[100:103], v[36:39]
	v_mfma_f32_16x16x32_bf16 v[48:51], v[144:147], v[104:107], v[48:51]
	v_mfma_f32_16x16x32_bf16 v[44:47], v[140:143], v[104:107], v[44:47]
	v_mfma_f32_16x16x32_bf16 v[40:43], v[136:139], v[104:107], v[40:43]
	v_mfma_f32_16x16x32_bf16 v[36:39], v[124:127], v[104:107], v[36:39]
	s_waitcnt lgkmcnt(0)
	v_mfma_f32_16x16x32_bf16 v[96:99], v[136:139], v[166:169], v[96:99]
	v_mfma_f32_16x16x32_bf16 v[92:95], v[124:127], v[166:169], v[92:95]
	v_mfma_f32_16x16x32_bf16 v[88:91], v[120:123], v[166:169], v[88:91]
	v_mfma_f32_16x16x32_bf16 v[84:87], v[108:111], v[166:169], v[84:87]
	v_mfma_f32_16x16x32_bf16 v[96:99], v[144:147], v[170:173], v[96:99]
	v_mfma_f32_16x16x32_bf16 v[92:95], v[140:143], v[170:173], v[92:95]
	v_mfma_f32_16x16x32_bf16 v[88:91], v[136:139], v[170:173], v[88:91]
	v_mfma_f32_16x16x32_bf16 v[84:87], v[124:127], v[170:173], v[84:87]
	s_addk_i32 s9, 0xff80
	s_add_i32 s8, s8, -1
	s_cmpk_lg_i32 s9, 0xee80
	s_cbranch_scc1 .Lhyb_b835
	s_branch .LBB0_843

; template <int LSEL>
; __device__ __forceinline__ void hy_conv(const bf16_t* Z, const bf16_t* G, f32x4 (&acc)[4][4], int w, int lane) {
;     ...
;   for (int d = i_lo - (NB - 1); d <= i_hi; ++d) {
;     bf16x8 bf[4][2];
; #pragma unroll
;     for (int k = 0; k < 4; ++k) {
;       int js = (q0 + k) * BPT - d;
;       js = min(max(js, LSEL ? -1 : 0), NB - 1);
;       const bf16_t* bp = Z + zb + 64 * js;
;       bf[k][0] = *(const bf16x8*)bp;
;       bf[k][1] = *(const bf16x8*)(bp + 32);
;     }
;     const bf16_t* gb = G + (L - 64 * d + 8 * quad - r - s);
;     bf16x8 F[6];
; #pragma unroll
;     for (int u = 0; u < 6; ++u) F[u] = hy_afrag(gb + 16 * (u - 3), t2, t1, sh);
; #pragma unroll
;     for (int k = 0; k < 4; ++k) {
;       const int js = (q0 + k) * BPT - d;
;       const bool valid = LSEL ? (js >= -1 && js <= NB - 1) : (js >= 0 && js <= NB - 1);
;       if (valid) {
; #pragma unroll
;         for (int mt = 0; mt < 4; ++mt) {
;           acc[k][mt] = __builtin_amdgcn_mfma_f32_16x16x32_bf16(F[3 - mt], bf[k][0], acc[k][mt], 0, 0, 0);
;           acc[k][mt] = __builtin_amdgcn_mfma_f32_16x16x32_bf16(F[5 - mt], bf[k][1], acc[k][mt], 0, 0, 0);
;         }
;       }
;     }
.Lhyb_b835:
	v_add_u32_e32 v0, s9, v176
	ds_read2_b32 v[140:141], v0 offset1:1
	ds_read2_b32 v[142:143], v0 offset0:2 offset1:3
	ds_read_b32 v2, v0 offset:16
	ds_read2_b32 v[144:145], v0 offset0:8 offset1:9
	ds_read2_b32 v[146:147], v0 offset0:10 offset1:11
	ds_read_b32 v3, v0 offset:48
	ds_read2_b32 v[236:237], v0 offset0:16 offset1:17
	ds_read2_b32 v[238:239], v0 offset0:18 offset1:19
	ds_read_b32 v177, v0 offset:80
	ds_read2_b32 v[240:241], v0 offset0:24 offset1:25
	ds_read2_b32 v[242:243], v0 offset0:26 offset1:27
	ds_read_b32 v178, v0 offset:112
	s_add_i32 s12, s8, 1
	v_med3_i32 v0, s12, 0, 31
	v_lshl_add_u32 v0, v0, 7, v153
	s_add_i32 s11, s8, 2
	ds_read_b128 v[128:131], v0
	ds_read_b128 v[132:135], v0 offset:64
	s_waitcnt lgkmcnt(11)
	v_alignbit_b32 v140, v141, v140, v152
	v_alignbit_b32 v141, v142, v141, v152
	v_alignbit_b32 v142, v143, v142, v152
	v_alignbit_b32 v143, v2, v143, v152
	v_med3_i32 v0, s11, 0, 31
	s_add_i32 s10, s8, 3
	v_lshl_add_u32 v0, v0, 7, v153
	s_min_u32 s13, s10, 31
	ds_read_b128 v[112:115], v0
	ds_read_b128 v[116:119], v0 offset:64
	s_waitcnt lgkmcnt(10)
	v_alignbit_b32 v144, v145, v144, v152
	v_alignbit_b32 v145, v146, v145, v152
	v_alignbit_b32 v146, v147, v146, v152
	v_alignbit_b32 v147, v3, v147, v152
	v_lshl_add_u32 v0, s13, 7, v153
	ds_read_b128 v[100:103], v0
	ds_read_b128 v[104:107], v0 offset:64
	s_waitcnt lgkmcnt(9)
	v_alignbit_b32 v236, v237, v236, v152
	v_alignbit_b32 v237, v238, v237, v152
	v_alignbit_b32 v238, v239, v238, v152
	v_alignbit_b32 v239, v177, v239, v152
	s_waitcnt lgkmcnt(6)
	v_alignbit_b32 v240, v241, v240, v152
	v_alignbit_b32 v241, v242, v241, v152
	v_alignbit_b32 v242, v243, v242, v152
	v_alignbit_b32 v243, v178, v243, v152
	s_waitcnt lgkmcnt(0)
	s_cmp_lt_u32 s8, 29
	s_cbranch_scc0 .Lhyb_s835
	v_add_u32_e32 v0, s9, v154
	ds_read_b128 v[166:169], v0
	ds_read_b128 v[170:173], v0 offset:64
	v_mfma_f32_16x16x32_bf16 v[64:67], v[240:243], v[112:115], v[64:67]
	v_mfma_f32_16x16x32_bf16 v[60:63], v[236:239], v[112:115], v[60:63]
	v_mfma_f32_16x16x32_bf16 v[56:59], v[144:147], v[112:115], v[56:59]
	v_mfma_f32_16x16x32_bf16 v[52:55], v[140:143], v[112:115], v[52:55]
	v_mfma_f32_16x16x32_bf16 v[64:67], v[120:123], v[116:119], v[64:67]
	v_mfma_f32_16x16x32_bf16 v[60:63], v[108:111], v[116:119], v[60:63]
	v_mfma_f32_16x16x32_bf16 v[56:59], v[240:243], v[116:119], v[56:59]
	v_mfma_f32_16x16x32_bf16 v[52:55], v[236:239], v[116:119], v[52:55]
	v_mfma_f32_16x16x32_bf16 v[80:83], v[240:243], v[128:131], v[80:83]
	v_mfma_f32_16x16x32_bf16 v[76:79], v[236:239], v[128:131], v[76:79]
	v_mfma_f32_16x16x32_bf16 v[72:75], v[144:147], v[128:131], v[72:75]
	v_mfma_f32_16x16x32_bf16 v[68:71], v[140:143], v[128:131], v[68:71]
	v_mfma_f32_16x16x32_bf16 v[80:83], v[120:123], v[132:135], v[80:83]
	v_mfma_f32_16x16x32_bf16 v[76:79], v[108:111], v[132:135], v[76:79]
	v_mfma_f32_16x16x32_bf16 v[72:75], v[240:243], v[132:135], v[72:75]
	v_mfma_f32_16x16x32_bf16 v[68:71], v[236:239], v[132:135], v[68:71]
	v_mfma_f32_16x16x32_bf16 v[48:51], v[240:243], v[100:103], v[48:51]
	v_mfma_f32_16x16x32_bf16 v[44:47], v[236:239], v[100:103], v[44:47]
	v_mfma_f32_16x16x32_bf16 v[40:43], v[144:147], v[100:103], v[40:43]
	v_mfma_f32_16x16x32_bf16 v[36:39], v[140:143], v[100:103], v[36:39]
	v_mfma_f32_16x16x32_bf16 v[48:51], v[120:123], v[104:107], v[48:51]
	v_mfma_f32_16x16x32_bf16 v[44:47], v[108:111], v[104:107], v[44:47]
	v_mfma_f32_16x16x32_bf16 v[40:43], v[240:243], v[104:107], v[40:43]
	v_mfma_f32_16x16x32_bf16 v[36:39], v[236:239], v[104:107], v[36:39]
	s_waitcnt lgkmcnt(0)
	v_mfma_f32_16x16x32_bf16 v[96:99], v[240:243], v[166:169], v[96:99]
	v_mfma_f32_16x16x32_bf16 v[92:95], v[236:239], v[166:169], v[92:95]
	v_mfma_f32_16x16x32_bf16 v[88:91], v[144:147], v[166:169], v[88:91]
	v_mfma_f32_16x16x32_bf16 v[84:87], v[140:143], v[166:169], v[84:87]
	v_mfma_f32_16x16x32_bf16 v[96:99], v[120:123], v[170:173], v[96:99]
	v_mfma_f32_16x16x32_bf16 v[92:95], v[108:111], v[170:173], v[92:95]
	v_mfma_f32_16x16x32_bf16 v[88:91], v[240:243], v[170:173], v[88:91]
	v_mfma_f32_16x16x32_bf16 v[84:87], v[236:239], v[170:173], v[84:87]
	s_addk_i32 s9, 0xff80
	s_add_i32 s8, s8, -1
	s_cmpk_lg_i32 s9, 0xee80
	s_cbranch_scc1 .LBB0_835
	s_branch .LBB0_843
.Lhyb_s835:
	s_cmp_gt_u32 s8, 31
	s_cbranch_scc1 .Lhyb_b839
	v_add_u32_e32 v0, s9, v154
	ds_read_b128 v[166:169], v0
	ds_read_b128 v[170:173], v0 offset:64
	s_waitcnt lgkmcnt(1)
	v_mfma_f32_16x16x32_bf16 v[96:99], v[240:243], v[166:169], v[96:99]
	v_mfma_f32_16x16x32_bf16 v[92:95], v[236:239], v[166:169], v[92:95]
	v_mfma_f32_16x16x32_bf16 v[88:91], v[144:147], v[166:169], v[88:91]
	v_mfma_f32_16x16x32_bf16 v[84:87], v[140:143], v[166:169], v[84:87]
	s_waitcnt lgkmcnt(0)
	v_mfma_f32_16x16x32_bf16 v[96:99], v[120:123], v[170:173], v[96:99]
	v_mfma_f32_16x16x32_bf16 v[92:95], v[108:111], v[170:173], v[92:95]
	v_mfma_f32_16x16x32_bf16 v[88:91], v[240:243], v[170:173], v[88:91]
	v_mfma_f32_16x16x32_bf16 v[84:87], v[236:239], v[170:173], v[84:87]
	s_cmp_gt_u32 s12, 31
	s_cbranch_scc0 .Lhyb_b840

; template <int LSEL>
; __device__ __forceinline__ void hy_conv(const bf16_t* Z, const bf16_t* G, f32x4 (&acc)[4][4], int w, int lane) {
;     ...
; #pragma unroll
;     for (int k = 0; k < 4; ++k) {
;       const int js = (q0 + k) * BPT - d;
;       const bool valid = LSEL ? (js >= -1 && js <= NB - 1) : (js >= 0 && js <= NB - 1);
;       if (valid) {
; #pragma unroll
;         for (int mt = 0; mt < 4; ++mt) {
;           acc[k][mt] = __builtin_amdgcn_mfma_f32_16x16x32_bf16(F[3 - mt], bf[k][0], acc[k][mt], 0, 0, 0);
;           acc[k][mt] = __builtin_amdgcn_mfma_f32_16x16x32_bf16(F[5 - mt], bf[k][1], acc[k][mt], 0, 0, 0);
;         }
;       }
.Lhyb_b838:
	v_mfma_f32_16x16x32_bf16 v[64:67], v[240:243], v[112:115], v[64:67]
	v_mfma_f32_16x16x32_bf16 v[60:63], v[236:239], v[112:115], v[60:63]
	v_mfma_f32_16x16x32_bf16 v[56:59], v[144:147], v[112:115], v[56:59]
	v_mfma_f32_16x16x32_bf16 v[52:55], v[140:143], v[112:115], v[52:55]
	v_mfma_f32_16x16x32_bf16 v[64:67], v[120:123], v[116:119], v[64:67]
	v_mfma_f32_16x16x32_bf16 v[60:63], v[108:111], v[116:119], v[60:63]
	v_mfma_f32_16x16x32_bf16 v[56:59], v[240:243], v[116:119], v[56:59]
	v_mfma_f32_16x16x32_bf16 v[52:55], v[236:239], v[116:119], v[52:55]
	s_cmp_gt_u32 s10, 31
	s_cbranch_scc1 .Lhyb_latch_835
	s_branch .Lhyb_b842

; template <int LSEL>
; __device__ __forceinline__ void hy_conv(const bf16_t* Z, const bf16_t* G, f32x4 (&acc)[4][4], int w, int lane) {
;     ...
; #pragma unroll
;     for (int k = 0; k < 4; ++k) {
;       const int js = (q0 + k) * BPT - d;
;       const bool valid = LSEL ? (js >= -1 && js <= NB - 1) : (js >= 0 && js <= NB - 1);
;       if (valid) {
; #pragma unroll
;         for (int mt = 0; mt < 4; ++mt) {
;           acc[k][mt] = __builtin_amdgcn_mfma_f32_16x16x32_bf16(F[3 - mt], bf[k][0], acc[k][mt], 0, 0, 0);
;           acc[k][mt] = __builtin_amdgcn_mfma_f32_16x16x32_bf16(F[5 - mt], bf[k][1], acc[k][mt], 0, 0, 0);
;         }
;       }
.Lhyb_b840:
	v_mfma_f32_16x16x32_bf16 v[80:83], v[240:243], v[128:131], v[80:83]
	v_mfma_f32_16x16x32_bf16 v[76:79], v[236:239], v[128:131], v[76:79]
	v_mfma_f32_16x16x32_bf16 v[72:75], v[144:147], v[128:131], v[72:75]
	v_mfma_f32_16x16x32_bf16 v[68:71], v[140:143], v[128:131], v[68:71]
	v_mfma_f32_16x16x32_bf16 v[80:83], v[120:123], v[132:135], v[80:83]
	v_mfma_f32_16x16x32_bf16 v[76:79], v[108:111], v[132:135], v[76:79]
	v_mfma_f32_16x16x32_bf16 v[72:75], v[240:243], v[132:135], v[72:75]
	v_mfma_f32_16x16x32_bf16 v[68:71], v[236:239], v[132:135], v[68:71]
	s_cmp_gt_u32 s11, 31
	s_cbranch_scc0 .Lhyb_b838

; template <int LSEL>
; __device__ __forceinline__ void hy_conv(const bf16_t* Z, const bf16_t* G, f32x4 (&acc)[4][4], int w, int lane) {
;     ...
; #pragma unroll
;     for (int k = 0; k < 4; ++k) {
;       const int js = (q0 + k) * BPT - d;
;       const bool valid = LSEL ? (js >= -1 && js <= NB - 1) : (js >= 0 && js <= NB - 1);
;       if (valid) {
; #pragma unroll
;         for (int mt = 0; mt < 4; ++mt) {
;           acc[k][mt] = __builtin_amdgcn_mfma_f32_16x16x32_bf16(F[3 - mt], bf[k][0], acc[k][mt], 0, 0, 0);
;           acc[k][mt] = __builtin_amdgcn_mfma_f32_16x16x32_bf16(F[5 - mt], bf[k][1], acc[k][mt], 0, 0, 0);
;         }
;       }
.Lhyb_b842:
	v_mfma_f32_16x16x32_bf16 v[48:51], v[240:243], v[100:103], v[48:51]
	v_mfma_f32_16x16x32_bf16 v[44:47], v[236:239], v[100:103], v[44:47]
	v_mfma_f32_16x16x32_bf16 v[40:43], v[144:147], v[100:103], v[40:43]
	v_mfma_f32_16x16x32_bf16 v[36:39], v[140:143], v[100:103], v[36:39]
	v_mfma_f32_16x16x32_bf16 v[48:51], v[120:123], v[104:107], v[48:51]
	v_mfma_f32_16x16x32_bf16 v[44:47], v[108:111], v[104:107], v[44:47]
	v_mfma_f32_16x16x32_bf16 v[40:43], v[240:243], v[104:107], v[40:43]
	v_mfma_f32_16x16x32_bf16 v[36:39], v[236:239], v[104:107], v[36:39]
	s_branch .Lhyb_latch_835

; template <int LSEL>
; __device__ __forceinline__ void hy_conv(const bf16_t* Z, const bf16_t* G, f32x4 (&acc)[4][4], int w, int lane) {
;   constexpr int L = HyC<LSEL>::L, NB = HyC<LSEL>::NB, BPT = HyC<LSEL>::BPT, RS = HyC<LSEL>::RS, PADF = HyC<LSEL>::PADF;
;   const int r = lane & 15, quad = lane >> 4;
;   const int zb = (LSEL ? (r & 7) * RS + (r >> 3) * 64 : r * RS) + PADF + quad * 8;
;   const int s = (8 - (r & 7)) & 7;
;   const bool t2 = (s & 4) != 0, t1 = (s & 2) != 0;
;   const unsigned sh = (s & 1) * 16;
;   const int q0 = w * 4;
;   const int i_lo = q0 * BPT, i_hi = (q0 + 4) * BPT - 1;
;   for (int d = i_lo - (NB - 1); d <= i_hi; ++d) {
;     bf16x8 bf[4][2];
; #pragma unroll
;     for (int k = 0; k < 4; ++k) {
;       int js = (q0 + k) * BPT - d;
;       js = min(max(js, LSEL ? -1 : 0), NB - 1);
;       const bf16_t* bp = Z + zb + 64 * js;
;       bf[k][0] = *(const bf16x8*)bp;
;       bf[k][1] = *(const bf16x8*)(bp + 32);
;     }
;     const bf16_t* gb = G + (L - 64 * d + 8 * quad - r - s);
;     bf16x8 F[6];
; #pragma unroll
;     for (int u = 0; u < 6; ++u) F[u] = hy_afrag(gb + 16 * (u - 3), t2, t1, sh);
; #pragma unroll
;     for (int k = 0; k < 4; ++k) {
;       const int js = (q0 + k) * BPT - d;
;       const bool valid = LSEL ? (js >= -1 && js <= NB - 1) : (js >= 0 && js <= NB - 1);
;       if (valid) {
; #pragma unroll
;         for (int mt = 0; mt < 4; ++mt) {
;           acc[k][mt] = __builtin_amdgcn_mfma_f32_16x16x32_bf16(F[3 - mt], bf[k][0], acc[k][mt], 0, 0, 0);
;           acc[k][mt] = __builtin_amdgcn_mfma_f32_16x16x32_bf16(F[5 - mt], bf[k][1], acc[k][mt], 0, 0, 0);
;         }
;       }
;     }
.LBB0_926:
	s_or_b64 exec, exec, s[8:9]
	v_mov_b32_e32 v2, v1
	v_mov_b32_e32 v3, v1
	v_mov_b32_e32 v0, v1
	v_mov_b64_e32 v[6:7], v[2:3]
	v_mov_b64_e32 v[10:11], v[2:3]
	v_mov_b64_e32 v[14:15], v[2:3]
	v_mov_b64_e32 v[22:23], v[2:3]
	v_mov_b64_e32 v[26:27], v[2:3]
	v_mov_b64_e32 v[30:31], v[2:3]
	v_mov_b64_e32 v[34:35], v[2:3]
	v_mov_b64_e32 v[38:39], v[2:3]
	v_mov_b64_e32 v[42:43], v[2:3]
	v_mov_b64_e32 v[50:51], v[2:3]
	v_mov_b64_e32 v[54:55], v[2:3]
	v_mov_b64_e32 v[58:59], v[2:3]
	v_mov_b64_e32 v[62:63], v[2:3]
	v_mov_b64_e32 v[66:67], v[2:3]
	v_mov_b64_e32 v[70:71], v[2:3]
	v_mov_b64_e32 v[78:79], v[2:3]
	s_mov_b32 s8, 0
	s_mov_b32 s9, 31
	v_mov_b64_e32 v[4:5], v[0:1]
	v_mov_b64_e32 v[8:9], v[0:1]
	v_mov_b64_e32 v[12:13], v[0:1]
	v_mov_b64_e32 v[20:21], v[0:1]
	v_mov_b64_e32 v[24:25], v[0:1]
	v_mov_b64_e32 v[28:29], v[0:1]
	v_mov_b64_e32 v[32:33], v[0:1]
	v_mov_b64_e32 v[36:37], v[0:1]
	v_mov_b64_e32 v[40:41], v[0:1]
	v_mov_b64_e32 v[48:49], v[0:1]
	v_mov_b64_e32 v[52:53], v[0:1]
	v_mov_b64_e32 v[56:57], v[0:1]
	v_mov_b64_e32 v[60:61], v[0:1]
	v_mov_b64_e32 v[64:65], v[0:1]
	v_mov_b64_e32 v[68:69], v[0:1]
	v_mov_b64_e32 v[76:77], v[0:1]
	s_waitcnt lgkmcnt(0)
	s_barrier
	ds_read2_b32 v[108:109], v176 offset0:32 offset1:33
	ds_read2_b32 v[110:111], v176 offset0:34 offset1:35
	ds_read_b32 v2, v176 offset:144
	ds_read2_b32 v[120:121], v176 offset0:40 offset1:41
	ds_read2_b32 v[122:123], v176 offset0:42 offset1:43
	ds_read_b32 v3, v176 offset:176
	s_waitcnt lgkmcnt(0)
	v_alignbit_b32 v140, v109, v108, v152
	v_alignbit_b32 v141, v110, v109, v152
	v_alignbit_b32 v142, v111, v110, v152
	v_alignbit_b32 v143, v2, v111, v152
	v_alignbit_b32 v144, v121, v120, v152
	v_alignbit_b32 v145, v122, v121, v152
	v_alignbit_b32 v146, v123, v122, v152
	v_alignbit_b32 v147, v3, v123, v152
	s_branch .LBB0_928
.LBB0_927:
	s_addk_i32 s8, 0xff80
	s_add_i32 s9, s9, -1
	s_cmpk_lg_i32 s8, 0xee80
	s_cbranch_scc0 .LBB0_936
	s_branch .Lhyb_b928
.LBB0_928:
	v_add_u32_e32 v0, s8, v176
	ds_read2_b32 v[108:109], v0 offset1:1
	ds_read2_b32 v[110:111], v0 offset0:2 offset1:3
	ds_read_b32 v2, v0 offset:16
	ds_read2_b32 v[120:121], v0 offset0:8 offset1:9
	ds_read2_b32 v[122:123], v0 offset0:10 offset1:11
	ds_read_b32 v3, v0 offset:48
	ds_read2_b32 v[124:125], v0 offset0:16 offset1:17
	ds_read2_b32 v[126:127], v0 offset0:18 offset1:19
	ds_read_b32 v177, v0 offset:80
	ds_read2_b32 v[136:137], v0 offset0:24 offset1:25
	ds_read2_b32 v[138:139], v0 offset0:26 offset1:27
	ds_read_b32 v178, v0 offset:112
	s_add_i32 s12, s9, 1
	v_med3_i32 v0, s12, 0, 31
	v_lshl_add_u32 v0, v0, 7, v153
	s_add_i32 s11, s9, 2
	ds_read_b128 v[128:131], v0
	ds_read_b128 v[132:135], v0 offset:64
	s_waitcnt lgkmcnt(11)
	v_alignbit_b32 v108, v109, v108, v152
	v_alignbit_b32 v109, v110, v109, v152
	v_alignbit_b32 v110, v111, v110, v152
	v_alignbit_b32 v111, v2, v111, v152
	v_med3_i32 v0, s11, 0, 31
	s_add_i32 s10, s9, 3
	v_lshl_add_u32 v0, v0, 7, v153
	s_min_u32 s13, s10, 31
	ds_read_b128 v[112:115], v0
	ds_read_b128 v[116:119], v0 offset:64
	s_waitcnt lgkmcnt(10)
	v_alignbit_b32 v120, v121, v120, v152
	v_alignbit_b32 v121, v122, v121, v152
	v_alignbit_b32 v122, v123, v122, v152
	v_alignbit_b32 v123, v3, v123, v152
	v_lshl_add_u32 v0, s13, 7, v153
	ds_read_b128 v[100:103], v0
	ds_read_b128 v[104:107], v0 offset:64
	s_waitcnt lgkmcnt(9)
	v_alignbit_b32 v124, v125, v124, v152
	v_alignbit_b32 v125, v126, v125, v152
	v_alignbit_b32 v126, v127, v126, v152
	v_alignbit_b32 v127, v177, v127, v152
	s_waitcnt lgkmcnt(6)
	v_alignbit_b32 v136, v137, v136, v152
	v_alignbit_b32 v137, v138, v137, v152
	v_alignbit_b32 v138, v139, v138, v152
	v_alignbit_b32 v139, v178, v139, v152
	s_waitcnt lgkmcnt(0)
	s_cmp_lt_u32 s9, 29
	s_cbranch_scc0 .Lhy_slow_928
	v_add_u32_e32 v0, s8, v154
	ds_read_b128 v[166:169], v0
	ds_read_b128 v[170:173], v0 offset:64
	v_mfma_f32_16x16x32_bf16 v[36:39], v[136:139], v[112:115], v[36:39]
	v_mfma_f32_16x16x32_bf16 v[32:35], v[124:127], v[112:115], v[32:35]
	v_mfma_f32_16x16x32_bf16 v[28:31], v[120:123], v[112:115], v[28:31]
	v_mfma_f32_16x16x32_bf16 v[24:27], v[108:111], v[112:115], v[24:27]
	v_mfma_f32_16x16x32_bf16 v[36:39], v[144:147], v[116:119], v[36:39]
	v_mfma_f32_16x16x32_bf16 v[32:35], v[140:143], v[116:119], v[32:35]
	v_mfma_f32_16x16x32_bf16 v[28:31], v[136:139], v[116:119], v[28:31]
	v_mfma_f32_16x16x32_bf16 v[24:27], v[124:127], v[116:119], v[24:27]
	v_mfma_f32_16x16x32_bf16 v[56:59], v[136:139], v[128:131], v[56:59]
	v_mfma_f32_16x16x32_bf16 v[52:55], v[124:127], v[128:131], v[52:55]
	v_mfma_f32_16x16x32_bf16 v[48:51], v[120:123], v[128:131], v[48:51]
	v_mfma_f32_16x16x32_bf16 v[40:43], v[108:111], v[128:131], v[40:43]
	v_mfma_f32_16x16x32_bf16 v[56:59], v[144:147], v[132:135], v[56:59]
	v_mfma_f32_16x16x32_bf16 v[52:55], v[140:143], v[132:135], v[52:55]
	v_mfma_f32_16x16x32_bf16 v[48:51], v[136:139], v[132:135], v[48:51]
	v_mfma_f32_16x16x32_bf16 v[40:43], v[124:127], v[132:135], v[40:43]
	v_mfma_f32_16x16x32_bf16 v[20:23], v[136:139], v[100:103], v[20:23]
	v_mfma_f32_16x16x32_bf16 v[12:15], v[124:127], v[100:103], v[12:15]
	v_mfma_f32_16x16x32_bf16 v[8:11], v[120:123], v[100:103], v[8:11]
	v_mfma_f32_16x16x32_bf16 v[2:5], v[108:111], v[100:103], v[4:7]
	v_mfma_f32_16x16x32_bf16 v[20:23], v[144:147], v[104:107], v[20:23]
	v_mfma_f32_16x16x32_bf16 v[12:15], v[140:143], v[104:107], v[12:15]
	v_mfma_f32_16x16x32_bf16 v[8:11], v[136:139], v[104:107], v[8:11]
	v_mfma_f32_16x16x32_bf16 v[4:7], v[124:127], v[104:107], v[2:5]
	s_waitcnt lgkmcnt(0)
	v_mfma_f32_16x16x32_bf16 v[76:79], v[136:139], v[166:169], v[76:79]
	v_mfma_f32_16x16x32_bf16 v[68:71], v[124:127], v[166:169], v[68:71]
	v_mfma_f32_16x16x32_bf16 v[64:67], v[120:123], v[166:169], v[64:67]
	v_mfma_f32_16x16x32_bf16 v[60:63], v[108:111], v[166:169], v[60:63]
	v_mfma_f32_16x16x32_bf16 v[76:79], v[144:147], v[170:173], v[76:79]
	v_mfma_f32_16x16x32_bf16 v[68:71], v[140:143], v[170:173], v[68:71]
	v_mfma_f32_16x16x32_bf16 v[64:67], v[136:139], v[170:173], v[64:67]
	v_mfma_f32_16x16x32_bf16 v[60:63], v[124:127], v[170:173], v[60:63]
	s_addk_i32 s8, 0xff80
	s_add_i32 s9, s9, -1
	s_cmpk_lg_i32 s8, 0xee80
	s_cbranch_scc1 .Lhyb_b928
	s_branch .LBB0_936

; __device__ __forceinline__ bf16x8 hy_afrag(const bf16_t* gbase, const bool t2, const bool t1, const unsigned sh) {
;   const uint4 lo = *(const uint4*)gbase, hi = *(const uint4*)(gbase + 8);
;   const unsigned x0 = t2 ? lo.z : lo.x, x1 = t2 ? lo.w : lo.y, x2 = t2 ? hi.x : lo.z, x3 = t2 ? hi.y : lo.w,
;                  x4 = t2 ? hi.z : hi.x, x5 = t2 ? hi.w : hi.y;
;   const unsigned y0 = t1 ? x1 : x0, y1 = t1 ? x2 : x1, y2 = t1 ? x3 : x2, y3 = t1 ? x4 : x3, y4 = t1 ? x5 : x4;
;   union { unsigned u[4]; bf16x8 v; } o;
;   o.u[0] = __builtin_amdgcn_alignbit(y1, y0, sh);
;   o.u[1] = __builtin_amdgcn_alignbit(y2, y1, sh);
;   o.u[2] = __builtin_amdgcn_alignbit(y3, y2, sh);
;   o.u[3] = __builtin_amdgcn_alignbit(y4, y3, sh);
;   return o.v;
; }
; template <int LSEL>
; __device__ __forceinline__ void hy_conv(const bf16_t* Z, const bf16_t* G, f32x4 (&acc)[4][4], int w, int lane) {
;     ...
;   for (int d = i_lo - (NB - 1); d <= i_hi; ++d) {
;     bf16x8 bf[4][2];
; #pragma unroll
;     for (int k = 0; k < 4; ++k) {
;       int js = (q0 + k) * BPT - d;
;       js = min(max(js, LSEL ? -1 : 0), NB - 1);
;       const bf16_t* bp = Z + zb + 64 * js;
;       bf[k][0] = *(const bf16x8*)bp;
;       bf[k][1] = *(const bf16x8*)(bp + 32);
;     }
;     const bf16_t* gb = G + (L - 64 * d + 8 * quad - r - s);
;     bf16x8 F[6];
; #pragma unroll
;     for (int u = 0; u < 6; ++u) F[u] = hy_afrag(gb + 16 * (u - 3), t2, t1, sh);
; #pragma unroll
;     for (int k = 0; k < 4; ++k) {
;       const int js = (q0 + k) * BPT - d;
;       const bool valid = LSEL ? (js >= -1 && js <= NB - 1) : (js >= 0 && js <= NB - 1);
;       if (valid) {
; #pragma unroll
;         for (int mt = 0; mt < 4; ++mt) {
;           acc[k][mt] = __builtin_amdgcn_mfma_f32_16x16x32_bf16(F[3 - mt], bf[k][0], acc[k][mt], 0, 0, 0);
;           acc[k][mt] = __builtin_amdgcn_mfma_f32_16x16x32_bf16(F[5 - mt], bf[k][1], acc[k][mt], 0, 0, 0);
;         }
;       }
;     }
;   }
.Lhyb_b928:
	v_add_u32_e32 v0, s8, v176
	ds_read2_b32 v[140:141], v0 offset1:1
	ds_read2_b32 v[142:143], v0 offset0:2 offset1:3
	ds_read_b32 v2, v0 offset:16
	ds_read2_b32 v[144:145], v0 offset0:8 offset1:9
	ds_read2_b32 v[146:147], v0 offset0:10 offset1:11
	ds_read_b32 v3, v0 offset:48
	ds_read2_b32 v[236:237], v0 offset0:16 offset1:17
	ds_read2_b32 v[238:239], v0 offset0:18 offset1:19
	ds_read_b32 v177, v0 offset:80
	ds_read2_b32 v[240:241], v0 offset0:24 offset1:25
	ds_read2_b32 v[242:243], v0 offset0:26 offset1:27
	ds_read_b32 v178, v0 offset:112
	s_add_i32 s12, s9, 1
	v_med3_i32 v0, s12, 0, 31
	v_lshl_add_u32 v0, v0, 7, v153
	s_add_i32 s11, s9, 2
	ds_read_b128 v[128:131], v0
	ds_read_b128 v[132:135], v0 offset:64
	s_waitcnt lgkmcnt(11)
	v_alignbit_b32 v140, v141, v140, v152
	v_alignbit_b32 v141, v142, v141, v152
	v_alignbit_b32 v142, v143, v142, v152
	v_alignbit_b32 v143, v2, v143, v152
	v_med3_i32 v0, s11, 0, 31
	s_add_i32 s10, s9, 3
	v_lshl_add_u32 v0, v0, 7, v153
	s_min_u32 s13, s10, 31
	ds_read_b128 v[112:115], v0
	ds_read_b128 v[116:119], v0 offset:64
	s_waitcnt lgkmcnt(10)
	v_alignbit_b32 v144, v145, v144, v152
	v_alignbit_b32 v145, v146, v145, v152
	v_alignbit_b32 v146, v147, v146, v152
	v_alignbit_b32 v147, v3, v147, v152
	v_lshl_add_u32 v0, s13, 7, v153
	ds_read_b128 v[100:103], v0
	ds_read_b128 v[104:107], v0 offset:64
	s_waitcnt lgkmcnt(9)
	v_alignbit_b32 v236, v237, v236, v152
	v_alignbit_b32 v237, v238, v237, v152
	v_alignbit_b32 v238, v239, v238, v152
	v_alignbit_b32 v239, v177, v239, v152
	s_waitcnt lgkmcnt(6)
	v_alignbit_b32 v240, v241, v240, v152
	v_alignbit_b32 v241, v242, v241, v152
	v_alignbit_b32 v242, v243, v242, v152
	v_alignbit_b32 v243, v178, v243, v152
	s_waitcnt lgkmcnt(0)
	s_cmp_lt_u32 s9, 29
	s_cbranch_scc0 .Lhyb_s928
	v_add_u32_e32 v0, s8, v154
	ds_read_b128 v[166:169], v0
	ds_read_b128 v[170:173], v0 offset:64
	v_mfma_f32_16x16x32_bf16 v[36:39], v[240:243], v[112:115], v[36:39]
	v_mfma_f32_16x16x32_bf16 v[32:35], v[236:239], v[112:115], v[32:35]
	v_mfma_f32_16x16x32_bf16 v[28:31], v[144:147], v[112:115], v[28:31]
	v_mfma_f32_16x16x32_bf16 v[24:27], v[140:143], v[112:115], v[24:27]
	v_mfma_f32_16x16x32_bf16 v[36:39], v[120:123], v[116:119], v[36:39]
	v_mfma_f32_16x16x32_bf16 v[32:35], v[108:111], v[116:119], v[32:35]
	v_mfma_f32_16x16x32_bf16 v[28:31], v[240:243], v[116:119], v[28:31]
	v_mfma_f32_16x16x32_bf16 v[24:27], v[236:239], v[116:119], v[24:27]
	v_mfma_f32_16x16x32_bf16 v[56:59], v[240:243], v[128:131], v[56:59]
	v_mfma_f32_16x16x32_bf16 v[52:55], v[236:239], v[128:131], v[52:55]
	v_mfma_f32_16x16x32_bf16 v[48:51], v[144:147], v[128:131], v[48:51]
	v_mfma_f32_16x16x32_bf16 v[40:43], v[140:143], v[128:131], v[40:43]
	v_mfma_f32_16x16x32_bf16 v[56:59], v[120:123], v[132:135], v[56:59]
	v_mfma_f32_16x16x32_bf16 v[52:55], v[108:111], v[132:135], v[52:55]
	v_mfma_f32_16x16x32_bf16 v[48:51], v[240:243], v[132:135], v[48:51]
	v_mfma_f32_16x16x32_bf16 v[40:43], v[236:239], v[132:135], v[40:43]
	v_mfma_f32_16x16x32_bf16 v[20:23], v[240:243], v[100:103], v[20:23]
	v_mfma_f32_16x16x32_bf16 v[12:15], v[236:239], v[100:103], v[12:15]
	v_mfma_f32_16x16x32_bf16 v[8:11], v[144:147], v[100:103], v[8:11]
	v_mfma_f32_16x16x32_bf16 v[2:5], v[140:143], v[100:103], v[4:7]
	v_mfma_f32_16x16x32_bf16 v[20:23], v[120:123], v[104:107], v[20:23]
	v_mfma_f32_16x16x32_bf16 v[12:15], v[108:111], v[104:107], v[12:15]
	v_mfma_f32_16x16x32_bf16 v[8:11], v[240:243], v[104:107], v[8:11]
	v_mfma_f32_16x16x32_bf16 v[4:7], v[236:239], v[104:107], v[2:5]
	s_waitcnt lgkmcnt(0)
	v_mfma_f32_16x16x32_bf16 v[76:79], v[240:243], v[166:169], v[76:79]
	v_mfma_f32_16x16x32_bf16 v[68:71], v[236:239], v[166:169], v[68:71]
	v_mfma_f32_16x16x32_bf16 v[64:67], v[144:147], v[166:169], v[64:67]
	v_mfma_f32_16x16x32_bf16 v[60:63], v[140:143], v[166:169], v[60:63]
	v_mfma_f32_16x16x32_bf16 v[76:79], v[120:123], v[170:173], v[76:79]
	v_mfma_f32_16x16x32_bf16 v[68:71], v[108:111], v[170:173], v[68:71]
	v_mfma_f32_16x16x32_bf16 v[64:67], v[240:243], v[170:173], v[64:67]
	v_mfma_f32_16x16x32_bf16 v[60:63], v[236:239], v[170:173], v[60:63]
	s_addk_i32 s8, 0xff80
	s_add_i32 s9, s9, -1
	s_cmpk_lg_i32 s8, 0xee80
	s_cbranch_scc1 .LBB0_928
	s_branch .LBB0_936
.Lhyb_s928:
	s_cmp_gt_u32 s9, 31
	s_cbranch_scc1 .Lhyb_b932
	v_add_u32_e32 v0, s8, v154
	ds_read_b128 v[166:169], v0
	ds_read_b128 v[170:173], v0 offset:64
	s_waitcnt lgkmcnt(1)
	v_mfma_f32_16x16x32_bf16 v[76:79], v[240:243], v[166:169], v[76:79]
	v_mfma_f32_16x16x32_bf16 v[68:71], v[236:239], v[166:169], v[68:71]
	v_mfma_f32_16x16x32_bf16 v[64:67], v[144:147], v[166:169], v[64:67]
	v_mfma_f32_16x16x32_bf16 v[60:63], v[140:143], v[166:169], v[60:63]
	s_waitcnt lgkmcnt(0)
	v_mfma_f32_16x16x32_bf16 v[76:79], v[120:123], v[170:173], v[76:79]
	v_mfma_f32_16x16x32_bf16 v[68:71], v[108:111], v[170:173], v[68:71]
	v_mfma_f32_16x16x32_bf16 v[64:67], v[240:243], v[170:173], v[64:67]
	v_mfma_f32_16x16x32_bf16 v[60:63], v[236:239], v[170:173], v[60:63]
	s_cmp_gt_u32 s12, 31
	s_cbranch_scc0 .Lhyb_b933

; template <int LSEL>
; __device__ __forceinline__ void hy_conv(const bf16_t* Z, const bf16_t* G, f32x4 (&acc)[4][4], int w, int lane) {
;     ...
;     for (int k = 0; k < 4; ++k) {
;       const int js = (q0 + k) * BPT - d;
;       const bool valid = LSEL ? (js >= -1 && js <= NB - 1) : (js >= 0 && js <= NB - 1);
;       if (valid) {
; #pragma unroll
;         for (int mt = 0; mt < 4; ++mt) {
;           acc[k][mt] = __builtin_amdgcn_mfma_f32_16x16x32_bf16(F[3 - mt], bf[k][0], acc[k][mt], 0, 0, 0);
;           acc[k][mt] = __builtin_amdgcn_mfma_f32_16x16x32_bf16(F[5 - mt], bf[k][1], acc[k][mt], 0, 0, 0);
;         }
;       }
;     }
.Lhyb_b931:
	v_mfma_f32_16x16x32_bf16 v[36:39], v[240:243], v[112:115], v[36:39]
	v_mfma_f32_16x16x32_bf16 v[32:35], v[236:239], v[112:115], v[32:35]
	v_mfma_f32_16x16x32_bf16 v[28:31], v[144:147], v[112:115], v[28:31]
	v_mfma_f32_16x16x32_bf16 v[24:27], v[140:143], v[112:115], v[24:27]
	v_mfma_f32_16x16x32_bf16 v[36:39], v[120:123], v[116:119], v[36:39]
	v_mfma_f32_16x16x32_bf16 v[32:35], v[108:111], v[116:119], v[32:35]
	v_mfma_f32_16x16x32_bf16 v[28:31], v[240:243], v[116:119], v[28:31]
	v_mfma_f32_16x16x32_bf16 v[24:27], v[236:239], v[116:119], v[24:27]
	s_cmp_gt_u32 s10, 31
	s_cbranch_scc1 .Lhyb_latch_928
	s_branch .Lhyb_b935

; template <int LSEL>
; __device__ __forceinline__ void hy_conv(const bf16_t* Z, const bf16_t* G, f32x4 (&acc)[4][4], int w, int lane) {
;     ...
;     for (int k = 0; k < 4; ++k) {
;       const int js = (q0 + k) * BPT - d;
;       const bool valid = LSEL ? (js >= -1 && js <= NB - 1) : (js >= 0 && js <= NB - 1);
;       if (valid) {
; #pragma unroll
;         for (int mt = 0; mt < 4; ++mt) {
;           acc[k][mt] = __builtin_amdgcn_mfma_f32_16x16x32_bf16(F[3 - mt], bf[k][0], acc[k][mt], 0, 0, 0);
;           acc[k][mt] = __builtin_amdgcn_mfma_f32_16x16x32_bf16(F[5 - mt], bf[k][1], acc[k][mt], 0, 0, 0);
;         }
;       }
;     }
.Lhyb_b933:
	v_mfma_f32_16x16x32_bf16 v[56:59], v[240:243], v[128:131], v[56:59]
	v_mfma_f32_16x16x32_bf16 v[52:55], v[236:239], v[128:131], v[52:55]
	v_mfma_f32_16x16x32_bf16 v[48:51], v[144:147], v[128:131], v[48:51]
	v_mfma_f32_16x16x32_bf16 v[40:43], v[140:143], v[128:131], v[40:43]
	v_mfma_f32_16x16x32_bf16 v[56:59], v[120:123], v[132:135], v[56:59]
	v_mfma_f32_16x16x32_bf16 v[52:55], v[108:111], v[132:135], v[52:55]
	v_mfma_f32_16x16x32_bf16 v[48:51], v[240:243], v[132:135], v[48:51]
	v_mfma_f32_16x16x32_bf16 v[40:43], v[236:239], v[132:135], v[40:43]
	s_cmp_gt_u32 s11, 31
	s_cbranch_scc0 .Lhyb_b931

; template <int LSEL>
; __device__ __forceinline__ void hy_conv(const bf16_t* Z, const bf16_t* G, f32x4 (&acc)[4][4], int w, int lane) {
;     ...
;     for (int k = 0; k < 4; ++k) {
;       const int js = (q0 + k) * BPT - d;
;       const bool valid = LSEL ? (js >= -1 && js <= NB - 1) : (js >= 0 && js <= NB - 1);
;       if (valid) {
; #pragma unroll
;         for (int mt = 0; mt < 4; ++mt) {
;           acc[k][mt] = __builtin_amdgcn_mfma_f32_16x16x32_bf16(F[3 - mt], bf[k][0], acc[k][mt], 0, 0, 0);
;           acc[k][mt] = __builtin_amdgcn_mfma_f32_16x16x32_bf16(F[5 - mt], bf[k][1], acc[k][mt], 0, 0, 0);
;         }
;       }
;     }
.Lhyb_b935:
	v_mfma_f32_16x16x32_bf16 v[20:23], v[240:243], v[100:103], v[20:23]
	v_mfma_f32_16x16x32_bf16 v[12:15], v[236:239], v[100:103], v[12:15]
	v_mfma_f32_16x16x32_bf16 v[8:11], v[144:147], v[100:103], v[8:11]
	v_mfma_f32_16x16x32_bf16 v[2:5], v[140:143], v[100:103], v[4:7]
	v_mfma_f32_16x16x32_bf16 v[20:23], v[120:123], v[104:107], v[20:23]
	v_mfma_f32_16x16x32_bf16 v[12:15], v[108:111], v[104:107], v[12:15]
	v_mfma_f32_16x16x32_bf16 v[8:11], v[240:243], v[104:107], v[8:11]
	v_mfma_f32_16x16x32_bf16 v[4:7], v[236:239], v[104:107], v[2:5]
	s_branch .Lhyb_latch_928

; template <int LSEL>
; __device__ __forceinline__ void hy_apply(const HyRaw& rw, float w0, float w1, float w2, float bias, bf16_t* dst, int toZ) {
;   constexpr int L = HyC<LSEL>::L, RS = HyC<LSEL>::RS, PADF = HyC<LSEL>::PADF;
;   const int tid = opaque_tid(), lane = tid & 63;
; #pragma unroll
;   for (int it = 0; it < 8; ++it) {
;     const int tok = (tid + 512 * it) * 8;
;     const int b = tok / L, s = tok - b * L;
;     const uint4 u = rw.u[it];
;     unsigned pw = (unsigned)__builtin_amdgcn_update_dpp(0, (int)u.w, 0x138, 0xf, 0xf, false);
;     unsigned nx = (unsigned)__builtin_amdgcn_update_dpp(0, (int)u.x, 0x130, 0xf, 0xf, false);
;     float x[10];
;     x[0] = hi2f(pw);
;     x[9] = lo2f(nx);
;     if (lane == 0) x[0] = bf2f(rw.edge[it]);
;     if (lane == 63) x[9] = bf2f(rw.edge[it]);
;     if (s == 0) x[0] = 0.f;
;     if (s + 8 >= L) x[9] = 0.f;
;     x[1] = lo2f(u.x); x[2] = hi2f(u.x); x[3] = lo2f(u.y); x[4] = hi2f(u.y);
;     x[5] = lo2f(u.z); x[6] = hi2f(u.z); x[7] = lo2f(u.w); x[8] = hi2f(u.w);
;     float o[8];
; #pragma unroll
;     for (int j = 0; j < 8; ++j) o[j] = w0 * x[j] + w1 * x[j + 1] + w2 * x[j + 2] + bias;
;     uint4 ou;
;     ou.x = pack2(o[0], o[1]); ou.y = pack2(o[2], o[3]); ou.z = pack2(o[4], o[5]); ou.w = pack2(o[6], o[7]);
;     *(uint4*)(dst + (toZ ? b * RS + PADF + s : b * HyC<LSEL>::XS + s)) = ou;
;   }
; }
; __device__ __forceinline__ bf16x8 hy_afrag(const bf16_t* gbase, const bool t2, const bool t1, const unsigned sh) {
;   const uint4 lo = *(const uint4*)gbase, hi = *(const uint4*)(gbase + 8);
;   const unsigned x0 = t2 ? lo.z : lo.x, x1 = t2 ? lo.w : lo.y, x2 = t2 ? hi.x : lo.z, x3 = t2 ? hi.y : lo.w,
;                  x4 = t2 ? hi.z : hi.x, x5 = t2 ? hi.w : hi.y;
;   const unsigned y0 = t1 ? x1 : x0, y1 = t1 ? x2 : x1, y2 = t1 ? x3 : x2, y3 = t1 ? x4 : x3, y4 = t1 ? x5 : x4;
;   union { unsigned u[4]; bf16x8 v; } o;
;   o.u[0] = __builtin_amdgcn_alignbit(y1, y0, sh);
;   o.u[1] = __builtin_amdgcn_alignbit(y2, y1, sh);
;   o.u[2] = __builtin_amdgcn_alignbit(y3, y2, sh);
;   o.u[3] = __builtin_amdgcn_alignbit(y4, y3, sh);
;   return o.v;
; }
; template <int LSEL>
; __device__ __forceinline__ void hy_conv(const bf16_t* Z, const bf16_t* G, f32x4 (&acc)[4][4], int w, int lane) {
;   constexpr int L = HyC<LSEL>::L, NB = HyC<LSEL>::NB, BPT = HyC<LSEL>::BPT, RS = HyC<LSEL>::RS, PADF = HyC<LSEL>::PADF;
.LBB0_1110:
	s_or_b64 exec, exec, s[6:7]
	v_add_u32_e32 v35, 0x7000, v74
	v_ashrrev_i32_e32 v36, 31, v35
	v_lshrrev_b32_e32 v36, 20, v36
	v_add_u32_e32 v37, v35, v36
	v_and_b32_e32 v48, 0xfffff000, v37
	v_and_b32_e32 v36, 0xffff0000, v3
	v_and_b32_e32 v39, 16, v3
	v_lshlrev_b32_e32 v3, 16, v3
	v_cmp_ne_u32_e64 s[4:5], v35, v48
	v_ashrrev_i32_e32 v46, 12, v37
	v_and_b32_e32 v38, 0xffff0000, v2
	v_sub_u32_e32 v37, v35, v48
	v_cndmask_b32_e64 v40, 0, v0, s[4:5]
	s_movk_i32 s4, 0xff8
	v_mov_b32_e32 v44, v3
	v_mov_b32_e32 v45, v36
	v_mov_b32_e32 v2, v38
	v_cmp_gt_i32_e64 s[4:5], s4, v37
	v_pk_mul_f32 v[44:45], v[72:73], v[44:45]
	v_and_b32_e32 v35, 16, v64
	v_cndmask_b32_e64 v37, 0, v34, s[4:5]
	v_and_b32_e32 v34, 0xffff0000, v63
	v_pk_fma_f32 v[44:45], v[60:61], v[2:3], v[44:45]
	v_lshlrev_b32_e32 v43, 16, v64
	v_mov_b32_e32 v42, v34
	v_pk_fma_f32 v[36:37], v[68:69], v[36:37], v[44:45]
	v_and_b32_e32 v44, 0xffff0000, v62
	v_lshlrev_b32_e32 v45, 16, v63
	v_pk_mov_b32 v[38:39], v[42:43], v[38:39] op_sel:[1,0]
	v_mov_b32_e32 v41, v44
	v_pk_mov_b32 v[34:35], v[44:45], v[34:35] op_sel:[1,0]
	v_lshlrev_b32_e32 v0, 16, v62
	v_pk_mul_f32 v[40:41], v[58:59], v[40:41]
	v_pk_mul_f32 v[34:35], v[72:73], v[34:35]
	v_pk_mul_f32 v[38:39], v[72:73], v[38:39]
	v_pk_fma_f32 v[40:41], v[70:71], v[0:1], v[40:41] op_sel_hi:[1,0,1]
	v_pk_fma_f32 v[34:35], v[60:61], v[44:45], v[34:35]
	v_pk_fma_f32 v[38:39], v[60:61], v[42:43], v[38:39]
	v_pk_fma_f32 v[40:41], v[68:69], v[44:45], v[40:41]
	v_pk_fma_f32 v[34:35], v[68:69], v[42:43], v[34:35]
	v_pk_fma_f32 v[2:3], v[68:69], v[2:3], v[38:39]
	v_sub_u32_e32 v0, v74, v48
	v_pk_add_f32 v[36:37], v[66:67], v[36:37]
	v_pk_add_f32 v[40:41], v[66:67], v[40:41]
	v_pk_add_f32 v[34:35], v[66:67], v[34:35]
	v_pk_add_f32 v[2:3], v[66:67], v[2:3]
	v_lshlrev_b32_e32 v0, 1, v0
	v_and_b32_e32 v47, 63, v4
	v_cvt_pk_bf16_f32 v37, v36, v37
	v_cvt_pk_bf16_f32 v36, v2, v3
	v_cvt_pk_bf16_f32 v35, v34, v35
	v_cvt_pk_bf16_f32 v34, v40, v41
	v_mad_i32_i24 v0, v46, s39, v0
	ds_write_b128 v0, v[34:37] offset:57472
	v_sub_u32_e32 v0, 0, v47
	v_and_b32_e32 v2, 4, v0
	v_cmp_eq_u32_e64 s[4:5], 0, v2
	v_and_b32_e32 v2, 2, v0
	v_and_b32_e32 v167, 64, v150
	v_and_b32_e32 v166, 7, v4
	v_cmp_eq_u32_e64 s[6:7], 0, v2
	v_lshlrev_b32_e32 v2, 1, v167
	v_mul_u32_u24_e32 v34, 0x2110, v166
	v_and_b32_e32 v35, 48, v4
	v_add3_u32 v154, v2, v34, v35
	v_lshlrev_b32_e32 v2, 4, v4
	v_lshlrev_b32_e32 v151, 4, v0
	v_and_b32_e32 v0, 7, v0
	v_and_b32_e32 v3, 15, v4
	v_and_b32_e32 v2, 0x80, v2
	v_ashrrev_i32_e32 v165, 6, v4
	v_mad_u32_u24 v2, v166, s39, v2
	s_movk_i32 s10, 0x2000
	v_add_lshl_u32 v0, v0, v3, 1
	v_add3_u32 v155, v2, v35, s10
	v_sub_u32_e32 v0, v35, v0
	v_lshlrev_b32_e32 v2, 10, v165
	v_sub_u32_e32 v156, v0, v2
	v_mov_b32_e32 v2, v1
	v_mov_b32_e32 v3, v1
	v_mov_b32_e32 v0, v1
	v_mov_b64_e32 v[36:37], v[2:3]
	v_mov_b64_e32 v[40:41], v[2:3]
	v_mov_b64_e32 v[44:45], v[2:3]
	v_mov_b64_e32 v[48:49], v[2:3]
	v_mov_b64_e32 v[52:53], v[2:3]
	v_mov_b64_e32 v[56:57], v[2:3]
	v_mov_b64_e32 v[60:61], v[2:3]
	v_mov_b64_e32 v[64:65], v[2:3]
	v_mov_b64_e32 v[68:69], v[2:3]
	v_mov_b64_e32 v[72:73], v[2:3]
	v_mov_b64_e32 v[76:77], v[2:3]
	v_mov_b64_e32 v[80:81], v[2:3]
	v_mov_b64_e32 v[84:85], v[2:3]
	v_mov_b64_e32 v[88:89], v[2:3]
	v_mov_b64_e32 v[92:93], v[2:3]
	v_mov_b64_e32 v[96:97], v[2:3]
	s_mov_b32 s8, 0
	s_mov_b32 s9, 64
	v_mov_b64_e32 v[34:35], v[0:1]
	v_mov_b64_e32 v[38:39], v[0:1]
	v_mov_b64_e32 v[42:43], v[0:1]
	v_mov_b64_e32 v[46:47], v[0:1]
	v_mov_b64_e32 v[50:51], v[0:1]
	v_mov_b64_e32 v[54:55], v[0:1]
	v_mov_b64_e32 v[58:59], v[0:1]
	v_mov_b64_e32 v[62:63], v[0:1]
	v_mov_b64_e32 v[66:67], v[0:1]
	v_mov_b64_e32 v[70:71], v[0:1]
	v_mov_b64_e32 v[74:75], v[0:1]
	v_mov_b64_e32 v[78:79], v[0:1]
	v_mov_b64_e32 v[82:83], v[0:1]
	v_mov_b64_e32 v[86:87], v[0:1]
	v_mov_b64_e32 v[90:91], v[0:1]
	v_mov_b64_e32 v[94:95], v[0:1]
	v_lshrrev_b32_e32 v176, 3, v151
	v_and_b32_e32 v176, 12, v176
	v_add_u32_e32 v176, v176, v156
	v_add_u32_e32 v176, 0x248a0, v176
	s_waitcnt lgkmcnt(0)
	s_barrier
	ds_read2_b32 v[106:107], v176 offset0:32 offset1:33
	ds_read2_b32 v[108:109], v176 offset0:34 offset1:35
	ds_read_b32 v2, v176 offset:144
	ds_read2_b32 v[118:119], v176 offset0:40 offset1:41
	ds_read2_b32 v[120:121], v176 offset0:42 offset1:43
	ds_read_b32 v3, v176 offset:176
	s_waitcnt lgkmcnt(0)
	v_alignbit_b32 v138, v107, v106, v151
	v_alignbit_b32 v139, v108, v107, v151
	v_alignbit_b32 v140, v109, v108, v151
	v_alignbit_b32 v141, v2, v109, v151
	v_alignbit_b32 v142, v119, v118, v151
	v_alignbit_b32 v143, v120, v119, v151
	v_alignbit_b32 v144, v121, v120, v151
	v_alignbit_b32 v145, v3, v121, v151
	s_branch .LBB0_1112
; template <int LSEL>
; __device__ __forceinline__ void hy_conv(const bf16_t* Z, const bf16_t* G, f32x4 (&acc)[4][4], int w, int lane) {
;     ...
;   for (int d = i_lo - (NB - 1); d <= i_hi; ++d) {
;     bf16x8 bf[4][2];
; #pragma unroll
;     for (int k = 0; k < 4; ++k) {
;       int js = (q0 + k) * BPT - d;
;       js = min(max(js, LSEL ? -1 : 0), NB - 1);
;       const bf16_t* bp = Z + zb + 64 * js;
;       bf[k][0] = *(const bf16x8*)bp;
;       bf[k][1] = *(const bf16x8*)(bp + 32);
;     }
;     const bf16_t* gb = G + (L - 64 * d + 8 * quad - r - s);
;     bf16x8 F[6];
; #pragma unroll
;     for (int u = 0; u < 6; ++u) F[u] = hy_afrag(gb + 16 * (u - 3), t2, t1, sh);
; #pragma unroll
;     for (int k = 0; k < 4; ++k) {
;       const int js = (q0 + k) * BPT - d;
;       const bool valid = LSEL ? (js >= -1 && js <= NB - 1) : (js >= 0 && js <= NB - 1);
;       if (valid) {
; #pragma unroll
;         for (int mt = 0; mt < 4; ++mt) {
;           acc[k][mt] = __builtin_amdgcn_mfma_f32_16x16x32_bf16(F[3 - mt], bf[k][0], acc[k][mt], 0, 0, 0);
;           acc[k][mt] = __builtin_amdgcn_mfma_f32_16x16x32_bf16(F[5 - mt], bf[k][1], acc[k][mt], 0, 0, 0);
;         }
;       }
;     }
;   }
.LBB0_1111:
	s_add_i32 s9, s9, -1
	s_addk_i32 s8, 0xff80
	s_cmpk_lg_i32 s8, 0xdc80
	s_cbranch_scc0 .LBB0_1120
	s_branch .Lhyb_b1112
.LBB0_1112:
	v_add_u32_e32 v0, s8, v176
	ds_read2_b32 v[106:107], v0 offset1:1
	ds_read2_b32 v[108:109], v0 offset0:2 offset1:3
	ds_read_b32 v2, v0 offset:16
	ds_read2_b32 v[118:119], v0 offset0:8 offset1:9
	ds_read2_b32 v[120:121], v0 offset0:10 offset1:11
	ds_read_b32 v3, v0 offset:48
	ds_read2_b32 v[122:123], v0 offset0:16 offset1:17
	ds_read2_b32 v[124:125], v0 offset0:18 offset1:19
	ds_read_b32 v177, v0 offset:80
	ds_read2_b32 v[134:135], v0 offset0:24 offset1:25
	ds_read2_b32 v[136:137], v0 offset0:26 offset1:27
	ds_read_b32 v178, v0 offset:112
	s_add_i32 s10, s9, 1
	v_med3_i32 v0, s10, -1, 63
	v_lshl_add_u32 v0, v0, 7, v154
	s_add_i32 s10, s9, 3
	ds_read_b128 v[126:129], v0 offset:128
	ds_read_b128 v[130:133], v0 offset:192
	s_waitcnt lgkmcnt(11)
	v_alignbit_b32 v106, v107, v106, v151
	v_alignbit_b32 v107, v108, v107, v151
	v_alignbit_b32 v108, v109, v108, v151
	v_alignbit_b32 v109, v2, v109, v151
	v_med3_i32 v0, s10, -1, 63
	s_add_i32 s10, s9, 5
	v_lshl_add_u32 v0, v0, 7, v154
	s_min_i32 s10, s10, 63
	ds_read_b128 v[110:113], v0 offset:128
	ds_read_b128 v[114:117], v0 offset:192
	s_waitcnt lgkmcnt(10)
	v_alignbit_b32 v118, v119, v118, v151
	v_alignbit_b32 v119, v120, v119, v151
	v_alignbit_b32 v120, v121, v120, v151
	v_alignbit_b32 v121, v3, v121, v151
	v_lshl_add_u32 v0, s10, 7, v154
	ds_read_b128 v[98:101], v0 offset:128
	ds_read_b128 v[102:105], v0 offset:192
	s_waitcnt lgkmcnt(9)
	v_alignbit_b32 v122, v123, v122, v151
	v_alignbit_b32 v123, v124, v123, v151
	v_alignbit_b32 v124, v125, v124, v151
	v_alignbit_b32 v125, v177, v125, v151
	s_waitcnt lgkmcnt(6)
	v_alignbit_b32 v134, v135, v134, v151
	v_alignbit_b32 v135, v136, v135, v151
	v_alignbit_b32 v136, v137, v136, v151
	v_alignbit_b32 v137, v178, v137, v151
	s_waitcnt lgkmcnt(0)
	s_cmp_lt_u32 s9, 59
	s_cbranch_scc0 .Lhy_slow_1112
	v_add_u32_e32 v0, s8, v155
	ds_read_b128 v[168:171], v0
	ds_read_b128 v[172:175], v0 offset:64
	v_mfma_f32_16x16x32_bf16 v[62:65], v[134:137], v[110:113], v[62:65]
	v_mfma_f32_16x16x32_bf16 v[58:61], v[122:125], v[110:113], v[58:61]
	v_mfma_f32_16x16x32_bf16 v[54:57], v[118:121], v[110:113], v[54:57]
	v_mfma_f32_16x16x32_bf16 v[50:53], v[106:109], v[110:113], v[50:53]
	v_mfma_f32_16x16x32_bf16 v[62:65], v[142:145], v[114:117], v[62:65]
	v_mfma_f32_16x16x32_bf16 v[58:61], v[138:141], v[114:117], v[58:61]
	v_mfma_f32_16x16x32_bf16 v[54:57], v[134:137], v[114:117], v[54:57]
	v_mfma_f32_16x16x32_bf16 v[50:53], v[122:125], v[114:117], v[50:53]
	v_mfma_f32_16x16x32_bf16 v[78:81], v[134:137], v[126:129], v[78:81]
	v_mfma_f32_16x16x32_bf16 v[74:77], v[122:125], v[126:129], v[74:77]
	v_mfma_f32_16x16x32_bf16 v[70:73], v[118:121], v[126:129], v[70:73]
	v_mfma_f32_16x16x32_bf16 v[66:69], v[106:109], v[126:129], v[66:69]
	v_mfma_f32_16x16x32_bf16 v[78:81], v[142:145], v[130:133], v[78:81]
	v_mfma_f32_16x16x32_bf16 v[74:77], v[138:141], v[130:133], v[74:77]
	v_mfma_f32_16x16x32_bf16 v[70:73], v[134:137], v[130:133], v[70:73]
	v_mfma_f32_16x16x32_bf16 v[66:69], v[122:125], v[130:133], v[66:69]
	v_mfma_f32_16x16x32_bf16 v[46:49], v[134:137], v[98:101], v[46:49]
	v_mfma_f32_16x16x32_bf16 v[42:45], v[122:125], v[98:101], v[42:45]
	v_mfma_f32_16x16x32_bf16 v[38:41], v[118:121], v[98:101], v[38:41]
	v_mfma_f32_16x16x32_bf16 v[34:37], v[106:109], v[98:101], v[34:37]
	v_mfma_f32_16x16x32_bf16 v[46:49], v[142:145], v[102:105], v[46:49]
	v_mfma_f32_16x16x32_bf16 v[42:45], v[138:141], v[102:105], v[42:45]
	v_mfma_f32_16x16x32_bf16 v[38:41], v[134:137], v[102:105], v[38:41]
	v_mfma_f32_16x16x32_bf16 v[34:37], v[122:125], v[102:105], v[34:37]
	s_waitcnt lgkmcnt(0)
	v_mfma_f32_16x16x32_bf16 v[94:97], v[134:137], v[168:171], v[94:97]
	v_mfma_f32_16x16x32_bf16 v[90:93], v[122:125], v[168:171], v[90:93]
	v_mfma_f32_16x16x32_bf16 v[86:89], v[118:121], v[168:171], v[86:89]
	v_mfma_f32_16x16x32_bf16 v[82:85], v[106:109], v[168:171], v[82:85]
	v_mfma_f32_16x16x32_bf16 v[94:97], v[142:145], v[172:175], v[94:97]
	v_mfma_f32_16x16x32_bf16 v[90:93], v[138:141], v[172:175], v[90:93]
	v_mfma_f32_16x16x32_bf16 v[86:89], v[134:137], v[172:175], v[86:89]
	v_mfma_f32_16x16x32_bf16 v[82:85], v[122:125], v[172:175], v[82:85]
	s_add_i32 s9, s9, -1
	s_addk_i32 s8, 0xff80
	s_cmpk_lg_i32 s8, 0xdc80
	s_cbranch_scc1 .Lhyb_b1112
	s_branch .LBB0_1120

; __device__ __forceinline__ bf16x8 hy_afrag(const bf16_t* gbase, const bool t2, const bool t1, const unsigned sh) {
;   const uint4 lo = *(const uint4*)gbase, hi = *(const uint4*)(gbase + 8);
;   const unsigned x0 = t2 ? lo.z : lo.x, x1 = t2 ? lo.w : lo.y, x2 = t2 ? hi.x : lo.z, x3 = t2 ? hi.y : lo.w,
;                  x4 = t2 ? hi.z : hi.x, x5 = t2 ? hi.w : hi.y;
;   const unsigned y0 = t1 ? x1 : x0, y1 = t1 ? x2 : x1, y2 = t1 ? x3 : x2, y3 = t1 ? x4 : x3, y4 = t1 ? x5 : x4;
;   union { unsigned u[4]; bf16x8 v; } o;
;   o.u[0] = __builtin_amdgcn_alignbit(y1, y0, sh);
;   o.u[1] = __builtin_amdgcn_alignbit(y2, y1, sh);
;   o.u[2] = __builtin_amdgcn_alignbit(y3, y2, sh);
;   o.u[3] = __builtin_amdgcn_alignbit(y4, y3, sh);
;   return o.v;
; }
; template <int LSEL>
; __device__ __forceinline__ void hy_conv(const bf16_t* Z, const bf16_t* G, f32x4 (&acc)[4][4], int w, int lane) {
;     ...
;   for (int d = i_lo - (NB - 1); d <= i_hi; ++d) {
;     bf16x8 bf[4][2];
; #pragma unroll
;     for (int k = 0; k < 4; ++k) {
;       int js = (q0 + k) * BPT - d;
;       js = min(max(js, LSEL ? -1 : 0), NB - 1);
;       const bf16_t* bp = Z + zb + 64 * js;
;       bf[k][0] = *(const bf16x8*)bp;
;       bf[k][1] = *(const bf16x8*)(bp + 32);
;     }
;     const bf16_t* gb = G + (L - 64 * d + 8 * quad - r - s);
;     bf16x8 F[6];
; #pragma unroll
;     for (int u = 0; u < 6; ++u) F[u] = hy_afrag(gb + 16 * (u - 3), t2, t1, sh);
; #pragma unroll
;     for (int k = 0; k < 4; ++k) {
;       const int js = (q0 + k) * BPT - d;
;       const bool valid = LSEL ? (js >= -1 && js <= NB - 1) : (js >= 0 && js <= NB - 1);
;       if (valid) {
; #pragma unroll
;         for (int mt = 0; mt < 4; ++mt) {
;           acc[k][mt] = __builtin_amdgcn_mfma_f32_16x16x32_bf16(F[3 - mt], bf[k][0], acc[k][mt], 0, 0, 0);
;           acc[k][mt] = __builtin_amdgcn_mfma_f32_16x16x32_bf16(F[5 - mt], bf[k][1], acc[k][mt], 0, 0, 0);
;         }
;       }
;     }
;   }
.Lhyb_b1112:
	v_add_u32_e32 v0, s8, v176
	ds_read2_b32 v[138:139], v0 offset1:1
	ds_read2_b32 v[140:141], v0 offset0:2 offset1:3
	ds_read_b32 v2, v0 offset:16
	ds_read2_b32 v[142:143], v0 offset0:8 offset1:9
	ds_read2_b32 v[144:145], v0 offset0:10 offset1:11
	ds_read_b32 v3, v0 offset:48
	ds_read2_b32 v[236:237], v0 offset0:16 offset1:17
	ds_read2_b32 v[238:239], v0 offset0:18 offset1:19
	ds_read_b32 v177, v0 offset:80
	ds_read2_b32 v[240:241], v0 offset0:24 offset1:25
	ds_read2_b32 v[242:243], v0 offset0:26 offset1:27
	ds_read_b32 v178, v0 offset:112
	s_add_i32 s10, s9, 1
	v_med3_i32 v0, s10, -1, 63
	v_lshl_add_u32 v0, v0, 7, v154
	s_add_i32 s10, s9, 3
	ds_read_b128 v[126:129], v0 offset:128
	ds_read_b128 v[130:133], v0 offset:192
	s_waitcnt lgkmcnt(11)
	v_alignbit_b32 v138, v139, v138, v151
	v_alignbit_b32 v139, v140, v139, v151
	v_alignbit_b32 v140, v141, v140, v151
	v_alignbit_b32 v141, v2, v141, v151
	v_med3_i32 v0, s10, -1, 63
	s_add_i32 s10, s9, 5
	v_lshl_add_u32 v0, v0, 7, v154
	s_min_i32 s10, s10, 63
	ds_read_b128 v[110:113], v0 offset:128
	ds_read_b128 v[114:117], v0 offset:192
	s_waitcnt lgkmcnt(10)
	v_alignbit_b32 v142, v143, v142, v151
	v_alignbit_b32 v143, v144, v143, v151
	v_alignbit_b32 v144, v145, v144, v151
	v_alignbit_b32 v145, v3, v145, v151
	v_lshl_add_u32 v0, s10, 7, v154
	ds_read_b128 v[98:101], v0 offset:128
	ds_read_b128 v[102:105], v0 offset:192
	s_waitcnt lgkmcnt(9)
	v_alignbit_b32 v236, v237, v236, v151
	v_alignbit_b32 v237, v238, v237, v151
	v_alignbit_b32 v238, v239, v238, v151
	v_alignbit_b32 v239, v177, v239, v151
	s_waitcnt lgkmcnt(6)
	v_alignbit_b32 v240, v241, v240, v151
	v_alignbit_b32 v241, v242, v241, v151
	v_alignbit_b32 v242, v243, v242, v151
	v_alignbit_b32 v243, v178, v243, v151
	s_waitcnt lgkmcnt(0)
	s_cmp_lt_u32 s9, 59
	s_cbranch_scc0 .Lhyb_s1112
	v_add_u32_e32 v0, s8, v155
	ds_read_b128 v[168:171], v0
	ds_read_b128 v[172:175], v0 offset:64
	v_mfma_f32_16x16x32_bf16 v[62:65], v[240:243], v[110:113], v[62:65]
	v_mfma_f32_16x16x32_bf16 v[58:61], v[236:239], v[110:113], v[58:61]
	v_mfma_f32_16x16x32_bf16 v[54:57], v[142:145], v[110:113], v[54:57]
	v_mfma_f32_16x16x32_bf16 v[50:53], v[138:141], v[110:113], v[50:53]
	v_mfma_f32_16x16x32_bf16 v[62:65], v[118:121], v[114:117], v[62:65]
	v_mfma_f32_16x16x32_bf16 v[58:61], v[106:109], v[114:117], v[58:61]
	v_mfma_f32_16x16x32_bf16 v[54:57], v[240:243], v[114:117], v[54:57]
	v_mfma_f32_16x16x32_bf16 v[50:53], v[236:239], v[114:117], v[50:53]
	v_mfma_f32_16x16x32_bf16 v[78:81], v[240:243], v[126:129], v[78:81]
	v_mfma_f32_16x16x32_bf16 v[74:77], v[236:239], v[126:129], v[74:77]
	v_mfma_f32_16x16x32_bf16 v[70:73], v[142:145], v[126:129], v[70:73]
	v_mfma_f32_16x16x32_bf16 v[66:69], v[138:141], v[126:129], v[66:69]
	v_mfma_f32_16x16x32_bf16 v[78:81], v[118:121], v[130:133], v[78:81]
	v_mfma_f32_16x16x32_bf16 v[74:77], v[106:109], v[130:133], v[74:77]
	v_mfma_f32_16x16x32_bf16 v[70:73], v[240:243], v[130:133], v[70:73]
	v_mfma_f32_16x16x32_bf16 v[66:69], v[236:239], v[130:133], v[66:69]
	v_mfma_f32_16x16x32_bf16 v[46:49], v[240:243], v[98:101], v[46:49]
	v_mfma_f32_16x16x32_bf16 v[42:45], v[236:239], v[98:101], v[42:45]
	v_mfma_f32_16x16x32_bf16 v[38:41], v[142:145], v[98:101], v[38:41]
	v_mfma_f32_16x16x32_bf16 v[34:37], v[138:141], v[98:101], v[34:37]
	v_mfma_f32_16x16x32_bf16 v[46:49], v[118:121], v[102:105], v[46:49]
	v_mfma_f32_16x16x32_bf16 v[42:45], v[106:109], v[102:105], v[42:45]
	v_mfma_f32_16x16x32_bf16 v[38:41], v[240:243], v[102:105], v[38:41]
	v_mfma_f32_16x16x32_bf16 v[34:37], v[236:239], v[102:105], v[34:37]
	s_waitcnt lgkmcnt(0)
	v_mfma_f32_16x16x32_bf16 v[94:97], v[240:243], v[168:171], v[94:97]
	v_mfma_f32_16x16x32_bf16 v[90:93], v[236:239], v[168:171], v[90:93]
	v_mfma_f32_16x16x32_bf16 v[86:89], v[142:145], v[168:171], v[86:89]
	v_mfma_f32_16x16x32_bf16 v[82:85], v[138:141], v[168:171], v[82:85]
	v_mfma_f32_16x16x32_bf16 v[94:97], v[118:121], v[172:175], v[94:97]
	v_mfma_f32_16x16x32_bf16 v[90:93], v[106:109], v[172:175], v[90:93]
	v_mfma_f32_16x16x32_bf16 v[86:89], v[240:243], v[172:175], v[86:89]
	v_mfma_f32_16x16x32_bf16 v[82:85], v[236:239], v[172:175], v[82:85]
	s_add_i32 s9, s9, -1
	s_addk_i32 s8, 0xff80
	s_cmpk_lg_i32 s8, 0xdc80
	s_cbranch_scc1 .LBB0_1112
	s_branch .LBB0_1120
.Lhyb_s1112:
	s_cmp_gt_u32 s9, 64
	s_cbranch_scc1 .Lhyb_b1116
	v_add_u32_e32 v0, s8, v155
	ds_read_b128 v[168:171], v0
	ds_read_b128 v[172:175], v0 offset:64
	s_waitcnt lgkmcnt(1)
	v_mfma_f32_16x16x32_bf16 v[94:97], v[240:243], v[168:171], v[94:97]
	v_mfma_f32_16x16x32_bf16 v[90:93], v[236:239], v[168:171], v[90:93]
	v_mfma_f32_16x16x32_bf16 v[86:89], v[142:145], v[168:171], v[86:89]
	v_mfma_f32_16x16x32_bf16 v[82:85], v[138:141], v[168:171], v[82:85]
	s_waitcnt lgkmcnt(0)
	v_mfma_f32_16x16x32_bf16 v[94:97], v[118:121], v[172:175], v[94:97]
	v_mfma_f32_16x16x32_bf16 v[90:93], v[106:109], v[172:175], v[90:93]
	v_mfma_f32_16x16x32_bf16 v[86:89], v[240:243], v[172:175], v[86:89]
	v_mfma_f32_16x16x32_bf16 v[82:85], v[236:239], v[172:175], v[82:85]
	s_add_i32 s10, s9, 2
	s_cmp_gt_u32 s10, 64
	s_cbranch_scc0 .Lhyb_b1117

; template <int LSEL>
; __device__ __forceinline__ void hy_conv(const bf16_t* Z, const bf16_t* G, f32x4 (&acc)[4][4], int w, int lane) {
;     ...
;     for (int k = 0; k < 4; ++k) {
;       const int js = (q0 + k) * BPT - d;
;       const bool valid = LSEL ? (js >= -1 && js <= NB - 1) : (js >= 0 && js <= NB - 1);
;       if (valid) {
; #pragma unroll
;         for (int mt = 0; mt < 4; ++mt) {
;           acc[k][mt] = __builtin_amdgcn_mfma_f32_16x16x32_bf16(F[3 - mt], bf[k][0], acc[k][mt], 0, 0, 0);
;           acc[k][mt] = __builtin_amdgcn_mfma_f32_16x16x32_bf16(F[5 - mt], bf[k][1], acc[k][mt], 0, 0, 0);
;         }
;       }
;     }
.Lhyb_b1115:
	v_mfma_f32_16x16x32_bf16 v[62:65], v[240:243], v[110:113], v[62:65]
	v_mfma_f32_16x16x32_bf16 v[58:61], v[236:239], v[110:113], v[58:61]
	v_mfma_f32_16x16x32_bf16 v[54:57], v[142:145], v[110:113], v[54:57]
	v_mfma_f32_16x16x32_bf16 v[50:53], v[138:141], v[110:113], v[50:53]
	v_mfma_f32_16x16x32_bf16 v[62:65], v[118:121], v[114:117], v[62:65]
	v_mfma_f32_16x16x32_bf16 v[58:61], v[106:109], v[114:117], v[58:61]
	v_mfma_f32_16x16x32_bf16 v[54:57], v[240:243], v[114:117], v[54:57]
	v_mfma_f32_16x16x32_bf16 v[50:53], v[236:239], v[114:117], v[50:53]
	s_add_i32 s10, s9, 6
	s_cmp_gt_u32 s10, 64
	s_cbranch_scc1 .Lhyb_latch_1112
	s_branch .Lhyb_b1119

; template <int LSEL>
; __device__ __forceinline__ void hy_conv(const bf16_t* Z, const bf16_t* G, f32x4 (&acc)[4][4], int w, int lane) {
;     ...
;     for (int k = 0; k < 4; ++k) {
;       const int js = (q0 + k) * BPT - d;
;       const bool valid = LSEL ? (js >= -1 && js <= NB - 1) : (js >= 0 && js <= NB - 1);
;       if (valid) {
; #pragma unroll
;         for (int mt = 0; mt < 4; ++mt) {
;           acc[k][mt] = __builtin_amdgcn_mfma_f32_16x16x32_bf16(F[3 - mt], bf[k][0], acc[k][mt], 0, 0, 0);
;           acc[k][mt] = __builtin_amdgcn_mfma_f32_16x16x32_bf16(F[5 - mt], bf[k][1], acc[k][mt], 0, 0, 0);
;         }
;       }
;     }
.Lhyb_b1117:
	v_mfma_f32_16x16x32_bf16 v[78:81], v[240:243], v[126:129], v[78:81]
	v_mfma_f32_16x16x32_bf16 v[74:77], v[236:239], v[126:129], v[74:77]
	v_mfma_f32_16x16x32_bf16 v[70:73], v[142:145], v[126:129], v[70:73]
	v_mfma_f32_16x16x32_bf16 v[66:69], v[138:141], v[126:129], v[66:69]
	v_mfma_f32_16x16x32_bf16 v[78:81], v[118:121], v[130:133], v[78:81]
	v_mfma_f32_16x16x32_bf16 v[74:77], v[106:109], v[130:133], v[74:77]
	v_mfma_f32_16x16x32_bf16 v[70:73], v[240:243], v[130:133], v[70:73]
	v_mfma_f32_16x16x32_bf16 v[66:69], v[236:239], v[130:133], v[66:69]
	s_add_i32 s10, s9, 4
	s_cmp_gt_u32 s10, 64
	s_cbranch_scc0 .Lhyb_b1115

; template <int LSEL>
; __device__ __forceinline__ void hy_conv(const bf16_t* Z, const bf16_t* G, f32x4 (&acc)[4][4], int w, int lane) {
;     ...
;     for (int k = 0; k < 4; ++k) {
;       const int js = (q0 + k) * BPT - d;
;       const bool valid = LSEL ? (js >= -1 && js <= NB - 1) : (js >= 0 && js <= NB - 1);
;       if (valid) {
; #pragma unroll
;         for (int mt = 0; mt < 4; ++mt) {
;           acc[k][mt] = __builtin_amdgcn_mfma_f32_16x16x32_bf16(F[3 - mt], bf[k][0], acc[k][mt], 0, 0, 0);
;           acc[k][mt] = __builtin_amdgcn_mfma_f32_16x16x32_bf16(F[5 - mt], bf[k][1], acc[k][mt], 0, 0, 0);
;         }
;       }
;     }
.Lhyb_b1119:
	v_mfma_f32_16x16x32_bf16 v[46:49], v[240:243], v[98:101], v[46:49]
	v_mfma_f32_16x16x32_bf16 v[42:45], v[236:239], v[98:101], v[42:45]
	v_mfma_f32_16x16x32_bf16 v[38:41], v[142:145], v[98:101], v[38:41]
	v_mfma_f32_16x16x32_bf16 v[34:37], v[138:141], v[98:101], v[34:37]
	v_mfma_f32_16x16x32_bf16 v[46:49], v[118:121], v[102:105], v[46:49]
	v_mfma_f32_16x16x32_bf16 v[42:45], v[106:109], v[102:105], v[42:45]
	v_mfma_f32_16x16x32_bf16 v[38:41], v[240:243], v[102:105], v[38:41]
	v_mfma_f32_16x16x32_bf16 v[34:37], v[236:239], v[102:105], v[34:37]
	s_branch .Lhyb_latch_1112

; __device__ __forceinline__ bf16x8 hy_afrag(const bf16_t* gbase, const bool t2, const bool t1, const unsigned sh) {
;   const uint4 lo = *(const uint4*)gbase, hi = *(const uint4*)(gbase + 8);
;   const unsigned x0 = t2 ? lo.z : lo.x, x1 = t2 ? lo.w : lo.y, x2 = t2 ? hi.x : lo.z, x3 = t2 ? hi.y : lo.w,
;                  x4 = t2 ? hi.z : hi.x, x5 = t2 ? hi.w : hi.y;
;   const unsigned y0 = t1 ? x1 : x0, y1 = t1 ? x2 : x1, y2 = t1 ? x3 : x2, y3 = t1 ? x4 : x3, y4 = t1 ? x5 : x4;
;   union { unsigned u[4]; bf16x8 v; } o;
;   o.u[0] = __builtin_amdgcn_alignbit(y1, y0, sh);
;   o.u[1] = __builtin_amdgcn_alignbit(y2, y1, sh);
;   o.u[2] = __builtin_amdgcn_alignbit(y3, y2, sh);
;   o.u[3] = __builtin_amdgcn_alignbit(y4, y3, sh);
;   return o.v;
; }
; template <int LSEL>
; __device__ __forceinline__ void hy_conv(const bf16_t* Z, const bf16_t* G, f32x4 (&acc)[4][4], int w, int lane) {
;     ...
;   for (int d = i_lo - (NB - 1); d <= i_hi; ++d) {
;     bf16x8 bf[4][2];
; #pragma unroll
;     for (int k = 0; k < 4; ++k) {
;       int js = (q0 + k) * BPT - d;
;       js = min(max(js, LSEL ? -1 : 0), NB - 1);
;       const bf16_t* bp = Z + zb + 64 * js;
;       bf[k][0] = *(const bf16x8*)bp;
;       bf[k][1] = *(const bf16x8*)(bp + 32);
;     }
;     const bf16_t* gb = G + (L - 64 * d + 8 * quad - r - s);
;     bf16x8 F[6];
; #pragma unroll
;     for (int u = 0; u < 6; ++u) F[u] = hy_afrag(gb + 16 * (u - 3), t2, t1, sh);
; #pragma unroll
;     for (int k = 0; k < 4; ++k) {
;       const int js = (q0 + k) * BPT - d;
;       const bool valid = LSEL ? (js >= -1 && js <= NB - 1) : (js >= 0 && js <= NB - 1);
;       if (valid) {
; #pragma unroll
;         for (int mt = 0; mt < 4; ++mt) {
;           acc[k][mt] = __builtin_amdgcn_mfma_f32_16x16x32_bf16(F[3 - mt], bf[k][0], acc[k][mt], 0, 0, 0);
;           acc[k][mt] = __builtin_amdgcn_mfma_f32_16x16x32_bf16(F[5 - mt], bf[k][1], acc[k][mt], 0, 0, 0);
;         }
;       }
;     }
;   }
.LBB0_1203:
	s_or_b64 exec, exec, s[8:9]
	v_mov_b32_e32 v2, v1
	v_mov_b32_e32 v3, v1
	v_mov_b32_e32 v0, v1
	v_mov_b64_e32 v[8:9], v[2:3]
	v_mov_b64_e32 v[12:13], v[2:3]
	v_mov_b64_e32 v[16:17], v[2:3]
	v_mov_b64_e32 v[20:21], v[2:3]
	v_mov_b64_e32 v[24:25], v[2:3]
	v_mov_b64_e32 v[28:29], v[2:3]
	v_mov_b64_e32 v[32:33], v[2:3]
	v_mov_b64_e32 v[36:37], v[2:3]
	v_mov_b64_e32 v[40:41], v[2:3]
	v_mov_b64_e32 v[48:49], v[2:3]
	v_mov_b64_e32 v[52:53], v[2:3]
	v_mov_b64_e32 v[56:57], v[2:3]
	v_mov_b64_e32 v[60:61], v[2:3]
	v_mov_b64_e32 v[64:65], v[2:3]
	v_mov_b64_e32 v[68:69], v[2:3]
	v_mov_b64_e32 v[76:77], v[2:3]
	s_mov_b32 s8, 64
	s_mov_b32 s9, 0
	v_mov_b64_e32 v[6:7], v[0:1]
	v_mov_b64_e32 v[10:11], v[0:1]
	v_mov_b64_e32 v[14:15], v[0:1]
	v_mov_b64_e32 v[18:19], v[0:1]
	v_mov_b64_e32 v[22:23], v[0:1]
	v_mov_b64_e32 v[26:27], v[0:1]
	v_mov_b64_e32 v[30:31], v[0:1]
	v_mov_b64_e32 v[34:35], v[0:1]
	v_mov_b64_e32 v[38:39], v[0:1]
	v_mov_b64_e32 v[46:47], v[0:1]
	v_mov_b64_e32 v[50:51], v[0:1]
	v_mov_b64_e32 v[54:55], v[0:1]
	v_mov_b64_e32 v[58:59], v[0:1]
	v_mov_b64_e32 v[62:63], v[0:1]
	v_mov_b64_e32 v[66:67], v[0:1]
	v_mov_b64_e32 v[74:75], v[0:1]
	s_waitcnt lgkmcnt(0)
	s_barrier
	ds_read2_b32 v[106:107], v176 offset0:32 offset1:33
	ds_read2_b32 v[108:109], v176 offset0:34 offset1:35
	ds_read_b32 v2, v176 offset:144
	ds_read2_b32 v[118:119], v176 offset0:40 offset1:41
	ds_read2_b32 v[120:121], v176 offset0:42 offset1:43
	ds_read_b32 v3, v176 offset:176
	s_waitcnt lgkmcnt(0)
	v_alignbit_b32 v138, v107, v106, v151
	v_alignbit_b32 v139, v108, v107, v151
	v_alignbit_b32 v140, v109, v108, v151
	v_alignbit_b32 v141, v2, v109, v151
	v_alignbit_b32 v142, v119, v118, v151
	v_alignbit_b32 v143, v120, v119, v151
	v_alignbit_b32 v144, v121, v120, v151
	v_alignbit_b32 v145, v3, v121, v151
	s_branch .LBB0_1205
.LBB0_1204:
	s_add_i32 s8, s8, -1
	s_addk_i32 s9, 0xff80
	s_cmpk_lg_i32 s9, 0xdc80
	s_cbranch_scc0 .LBB0_1213
	s_branch .Lhyb_b1205
.LBB0_1205:
	v_add_u32_e32 v0, s9, v176
	ds_read2_b32 v[106:107], v0 offset1:1
	ds_read2_b32 v[108:109], v0 offset0:2 offset1:3
	ds_read_b32 v2, v0 offset:16
	ds_read2_b32 v[118:119], v0 offset0:8 offset1:9
	ds_read2_b32 v[120:121], v0 offset0:10 offset1:11
	ds_read_b32 v3, v0 offset:48
	ds_read2_b32 v[122:123], v0 offset0:16 offset1:17
	ds_read2_b32 v[124:125], v0 offset0:18 offset1:19
	ds_read_b32 v177, v0 offset:80
	ds_read2_b32 v[134:135], v0 offset0:24 offset1:25
	ds_read2_b32 v[136:137], v0 offset0:26 offset1:27
	ds_read_b32 v178, v0 offset:112
	s_add_i32 s10, s8, 1
	v_med3_i32 v0, s10, -1, 63
	v_lshl_add_u32 v0, v0, 7, v154
	s_add_i32 s10, s8, 3
	ds_read_b128 v[126:129], v0 offset:128
	ds_read_b128 v[130:133], v0 offset:192
	s_waitcnt lgkmcnt(11)
	v_alignbit_b32 v106, v107, v106, v151
	v_alignbit_b32 v107, v108, v107, v151
	v_alignbit_b32 v108, v109, v108, v151
	v_alignbit_b32 v109, v2, v109, v151
	v_med3_i32 v0, s10, -1, 63
	s_add_i32 s10, s8, 5
	v_lshl_add_u32 v0, v0, 7, v154
	s_min_i32 s10, s10, 63
	ds_read_b128 v[110:113], v0 offset:128
	ds_read_b128 v[114:117], v0 offset:192
	s_waitcnt lgkmcnt(10)
	v_alignbit_b32 v118, v119, v118, v151
	v_alignbit_b32 v119, v120, v119, v151
	v_alignbit_b32 v120, v121, v120, v151
	v_alignbit_b32 v121, v3, v121, v151
	v_lshl_add_u32 v0, s10, 7, v154
	ds_read_b128 v[98:101], v0 offset:128
	ds_read_b128 v[102:105], v0 offset:192
	s_waitcnt lgkmcnt(9)
	v_alignbit_b32 v122, v123, v122, v151
	v_alignbit_b32 v123, v124, v123, v151
	v_alignbit_b32 v124, v125, v124, v151
	v_alignbit_b32 v125, v177, v125, v151
	s_waitcnt lgkmcnt(6)
	v_alignbit_b32 v134, v135, v134, v151
	v_alignbit_b32 v135, v136, v135, v151
	v_alignbit_b32 v136, v137, v136, v151
	v_alignbit_b32 v137, v178, v137, v151
	s_waitcnt lgkmcnt(0)
	s_cmp_lt_u32 s8, 59
	s_cbranch_scc0 .Lhy_slow_1205
	v_add_u32_e32 v0, s9, v155
	ds_read_b128 v[168:171], v0
	ds_read_b128 v[172:175], v0 offset:64
	v_mfma_f32_16x16x32_bf16 v[34:37], v[134:137], v[110:113], v[34:37]
	v_mfma_f32_16x16x32_bf16 v[30:33], v[122:125], v[110:113], v[30:33]
	v_mfma_f32_16x16x32_bf16 v[26:29], v[118:121], v[110:113], v[26:29]
	v_mfma_f32_16x16x32_bf16 v[22:25], v[106:109], v[110:113], v[22:25]
	v_mfma_f32_16x16x32_bf16 v[34:37], v[142:145], v[114:117], v[34:37]
	v_mfma_f32_16x16x32_bf16 v[30:33], v[138:141], v[114:117], v[30:33]
	v_mfma_f32_16x16x32_bf16 v[26:29], v[134:137], v[114:117], v[26:29]
	v_mfma_f32_16x16x32_bf16 v[22:25], v[122:125], v[114:117], v[22:25]
	v_mfma_f32_16x16x32_bf16 v[54:57], v[134:137], v[126:129], v[54:57]
	v_mfma_f32_16x16x32_bf16 v[50:53], v[122:125], v[126:129], v[50:53]
	v_mfma_f32_16x16x32_bf16 v[46:49], v[118:121], v[126:129], v[46:49]
	v_mfma_f32_16x16x32_bf16 v[38:41], v[106:109], v[126:129], v[38:41]
	v_mfma_f32_16x16x32_bf16 v[54:57], v[142:145], v[130:133], v[54:57]
	v_mfma_f32_16x16x32_bf16 v[50:53], v[138:141], v[130:133], v[50:53]
	v_mfma_f32_16x16x32_bf16 v[46:49], v[134:137], v[130:133], v[46:49]
	v_mfma_f32_16x16x32_bf16 v[38:41], v[122:125], v[130:133], v[38:41]
	v_mfma_f32_16x16x32_bf16 v[18:21], v[134:137], v[98:101], v[18:21]
	v_mfma_f32_16x16x32_bf16 v[14:17], v[122:125], v[98:101], v[14:17]
	v_mfma_f32_16x16x32_bf16 v[10:13], v[118:121], v[98:101], v[10:13]
	v_mfma_f32_16x16x32_bf16 v[6:9], v[106:109], v[98:101], v[6:9]
	v_mfma_f32_16x16x32_bf16 v[18:21], v[142:145], v[102:105], v[18:21]
	v_mfma_f32_16x16x32_bf16 v[14:17], v[138:141], v[102:105], v[14:17]
	v_mfma_f32_16x16x32_bf16 v[10:13], v[134:137], v[102:105], v[10:13]
	v_mfma_f32_16x16x32_bf16 v[6:9], v[122:125], v[102:105], v[6:9]
	s_waitcnt lgkmcnt(0)
	v_mfma_f32_16x16x32_bf16 v[74:77], v[134:137], v[168:171], v[74:77]
	v_mfma_f32_16x16x32_bf16 v[66:69], v[122:125], v[168:171], v[66:69]
	v_mfma_f32_16x16x32_bf16 v[62:65], v[118:121], v[168:171], v[62:65]
	v_mfma_f32_16x16x32_bf16 v[58:61], v[106:109], v[168:171], v[58:61]
	v_mfma_f32_16x16x32_bf16 v[74:77], v[142:145], v[172:175], v[74:77]
	v_mfma_f32_16x16x32_bf16 v[66:69], v[138:141], v[172:175], v[66:69]
	v_mfma_f32_16x16x32_bf16 v[62:65], v[134:137], v[172:175], v[62:65]
	v_mfma_f32_16x16x32_bf16 v[58:61], v[122:125], v[172:175], v[58:61]
	s_add_i32 s8, s8, -1
	s_addk_i32 s9, 0xff80
	s_cmpk_lg_i32 s9, 0xdc80
	s_cbranch_scc1 .Lhyb_b1205
	s_branch .LBB0_1213

; __device__ __forceinline__ bf16x8 hy_afrag(const bf16_t* gbase, const bool t2, const bool t1, const unsigned sh) {
;   const uint4 lo = *(const uint4*)gbase, hi = *(const uint4*)(gbase + 8);
;   const unsigned x0 = t2 ? lo.z : lo.x, x1 = t2 ? lo.w : lo.y, x2 = t2 ? hi.x : lo.z, x3 = t2 ? hi.y : lo.w,
;                  x4 = t2 ? hi.z : hi.x, x5 = t2 ? hi.w : hi.y;
;   const unsigned y0 = t1 ? x1 : x0, y1 = t1 ? x2 : x1, y2 = t1 ? x3 : x2, y3 = t1 ? x4 : x3, y4 = t1 ? x5 : x4;
;   union { unsigned u[4]; bf16x8 v; } o;
;   o.u[0] = __builtin_amdgcn_alignbit(y1, y0, sh);
;   o.u[1] = __builtin_amdgcn_alignbit(y2, y1, sh);
;   o.u[2] = __builtin_amdgcn_alignbit(y3, y2, sh);
;   o.u[3] = __builtin_amdgcn_alignbit(y4, y3, sh);
;   return o.v;
; }
; template <int LSEL>
; __device__ __forceinline__ void hy_conv(const bf16_t* Z, const bf16_t* G, f32x4 (&acc)[4][4], int w, int lane) {
;     ...
;   for (int d = i_lo - (NB - 1); d <= i_hi; ++d) {
;     bf16x8 bf[4][2];
; #pragma unroll
;     for (int k = 0; k < 4; ++k) {
;       int js = (q0 + k) * BPT - d;
;       js = min(max(js, LSEL ? -1 : 0), NB - 1);
;       const bf16_t* bp = Z + zb + 64 * js;
;       bf[k][0] = *(const bf16x8*)bp;
;       bf[k][1] = *(const bf16x8*)(bp + 32);
;     }
;     const bf16_t* gb = G + (L - 64 * d + 8 * quad - r - s);
;     bf16x8 F[6];
; #pragma unroll
;     for (int u = 0; u < 6; ++u) F[u] = hy_afrag(gb + 16 * (u - 3), t2, t1, sh);
; #pragma unroll
;     for (int k = 0; k < 4; ++k) {
;       const int js = (q0 + k) * BPT - d;
;       const bool valid = LSEL ? (js >= -1 && js <= NB - 1) : (js >= 0 && js <= NB - 1);
;       if (valid) {
; #pragma unroll
;         for (int mt = 0; mt < 4; ++mt) {
;           acc[k][mt] = __builtin_amdgcn_mfma_f32_16x16x32_bf16(F[3 - mt], bf[k][0], acc[k][mt], 0, 0, 0);
;           acc[k][mt] = __builtin_amdgcn_mfma_f32_16x16x32_bf16(F[5 - mt], bf[k][1], acc[k][mt], 0, 0, 0);
;         }
;       }
;     }
;   }
.Lhyb_b1205:
	v_add_u32_e32 v0, s9, v176
	ds_read2_b32 v[138:139], v0 offset1:1
	ds_read2_b32 v[140:141], v0 offset0:2 offset1:3
	ds_read_b32 v2, v0 offset:16
	ds_read2_b32 v[142:143], v0 offset0:8 offset1:9
	ds_read2_b32 v[144:145], v0 offset0:10 offset1:11
	ds_read_b32 v3, v0 offset:48
	ds_read2_b32 v[236:237], v0 offset0:16 offset1:17
	ds_read2_b32 v[238:239], v0 offset0:18 offset1:19
	ds_read_b32 v177, v0 offset:80
	ds_read2_b32 v[240:241], v0 offset0:24 offset1:25
	ds_read2_b32 v[242:243], v0 offset0:26 offset1:27
	ds_read_b32 v178, v0 offset:112
	s_add_i32 s10, s8, 1
	v_med3_i32 v0, s10, -1, 63
	v_lshl_add_u32 v0, v0, 7, v154
	s_add_i32 s10, s8, 3
	ds_read_b128 v[126:129], v0 offset:128
	ds_read_b128 v[130:133], v0 offset:192
	s_waitcnt lgkmcnt(11)
	v_alignbit_b32 v138, v139, v138, v151
	v_alignbit_b32 v139, v140, v139, v151
	v_alignbit_b32 v140, v141, v140, v151
	v_alignbit_b32 v141, v2, v141, v151
	v_med3_i32 v0, s10, -1, 63
	s_add_i32 s10, s8, 5
	v_lshl_add_u32 v0, v0, 7, v154
	s_min_i32 s10, s10, 63
	ds_read_b128 v[110:113], v0 offset:128
	ds_read_b128 v[114:117], v0 offset:192
	s_waitcnt lgkmcnt(10)
	v_alignbit_b32 v142, v143, v142, v151
	v_alignbit_b32 v143, v144, v143, v151
	v_alignbit_b32 v144, v145, v144, v151
	v_alignbit_b32 v145, v3, v145, v151
	v_lshl_add_u32 v0, s10, 7, v154
	ds_read_b128 v[98:101], v0 offset:128
	ds_read_b128 v[102:105], v0 offset:192
	s_waitcnt lgkmcnt(9)
	v_alignbit_b32 v236, v237, v236, v151
	v_alignbit_b32 v237, v238, v237, v151
	v_alignbit_b32 v238, v239, v238, v151
	v_alignbit_b32 v239, v177, v239, v151
	s_waitcnt lgkmcnt(6)
	v_alignbit_b32 v240, v241, v240, v151
	v_alignbit_b32 v241, v242, v241, v151
	v_alignbit_b32 v242, v243, v242, v151
	v_alignbit_b32 v243, v178, v243, v151
	s_waitcnt lgkmcnt(0)
	s_cmp_lt_u32 s8, 59
	s_cbranch_scc0 .Lhyb_s1205
	v_add_u32_e32 v0, s9, v155
	ds_read_b128 v[168:171], v0
	ds_read_b128 v[172:175], v0 offset:64
	v_mfma_f32_16x16x32_bf16 v[34:37], v[240:243], v[110:113], v[34:37]
	v_mfma_f32_16x16x32_bf16 v[30:33], v[236:239], v[110:113], v[30:33]
	v_mfma_f32_16x16x32_bf16 v[26:29], v[142:145], v[110:113], v[26:29]
	v_mfma_f32_16x16x32_bf16 v[22:25], v[138:141], v[110:113], v[22:25]
	v_mfma_f32_16x16x32_bf16 v[34:37], v[118:121], v[114:117], v[34:37]
	v_mfma_f32_16x16x32_bf16 v[30:33], v[106:109], v[114:117], v[30:33]
	v_mfma_f32_16x16x32_bf16 v[26:29], v[240:243], v[114:117], v[26:29]
	v_mfma_f32_16x16x32_bf16 v[22:25], v[236:239], v[114:117], v[22:25]
	v_mfma_f32_16x16x32_bf16 v[54:57], v[240:243], v[126:129], v[54:57]
	v_mfma_f32_16x16x32_bf16 v[50:53], v[236:239], v[126:129], v[50:53]
	v_mfma_f32_16x16x32_bf16 v[46:49], v[142:145], v[126:129], v[46:49]
	v_mfma_f32_16x16x32_bf16 v[38:41], v[138:141], v[126:129], v[38:41]
	v_mfma_f32_16x16x32_bf16 v[54:57], v[118:121], v[130:133], v[54:57]
	v_mfma_f32_16x16x32_bf16 v[50:53], v[106:109], v[130:133], v[50:53]
	v_mfma_f32_16x16x32_bf16 v[46:49], v[240:243], v[130:133], v[46:49]
	v_mfma_f32_16x16x32_bf16 v[38:41], v[236:239], v[130:133], v[38:41]
	v_mfma_f32_16x16x32_bf16 v[18:21], v[240:243], v[98:101], v[18:21]
	v_mfma_f32_16x16x32_bf16 v[14:17], v[236:239], v[98:101], v[14:17]
	v_mfma_f32_16x16x32_bf16 v[10:13], v[142:145], v[98:101], v[10:13]
	v_mfma_f32_16x16x32_bf16 v[6:9], v[138:141], v[98:101], v[6:9]
	v_mfma_f32_16x16x32_bf16 v[18:21], v[118:121], v[102:105], v[18:21]
	v_mfma_f32_16x16x32_bf16 v[14:17], v[106:109], v[102:105], v[14:17]
	v_mfma_f32_16x16x32_bf16 v[10:13], v[240:243], v[102:105], v[10:13]
	v_mfma_f32_16x16x32_bf16 v[6:9], v[236:239], v[102:105], v[6:9]
	s_waitcnt lgkmcnt(0)
	v_mfma_f32_16x16x32_bf16 v[74:77], v[240:243], v[168:171], v[74:77]
	v_mfma_f32_16x16x32_bf16 v[66:69], v[236:239], v[168:171], v[66:69]
	v_mfma_f32_16x16x32_bf16 v[62:65], v[142:145], v[168:171], v[62:65]
	v_mfma_f32_16x16x32_bf16 v[58:61], v[138:141], v[168:171], v[58:61]
	v_mfma_f32_16x16x32_bf16 v[74:77], v[118:121], v[172:175], v[74:77]
	v_mfma_f32_16x16x32_bf16 v[66:69], v[106:109], v[172:175], v[66:69]
	v_mfma_f32_16x16x32_bf16 v[62:65], v[240:243], v[172:175], v[62:65]
	v_mfma_f32_16x16x32_bf16 v[58:61], v[236:239], v[172:175], v[58:61]
	s_add_i32 s8, s8, -1
	s_addk_i32 s9, 0xff80
	s_cmpk_lg_i32 s9, 0xdc80
	s_cbranch_scc1 .LBB0_1205
	s_branch .LBB0_1213
.Lhyb_s1205:
	s_cmp_gt_u32 s8, 64
	s_cbranch_scc1 .Lhyb_b1209
	v_add_u32_e32 v0, s9, v155
	ds_read_b128 v[168:171], v0
	ds_read_b128 v[172:175], v0 offset:64
	s_waitcnt lgkmcnt(1)
	v_mfma_f32_16x16x32_bf16 v[74:77], v[240:243], v[168:171], v[74:77]
	v_mfma_f32_16x16x32_bf16 v[66:69], v[236:239], v[168:171], v[66:69]
	v_mfma_f32_16x16x32_bf16 v[62:65], v[142:145], v[168:171], v[62:65]
	v_mfma_f32_16x16x32_bf16 v[58:61], v[138:141], v[168:171], v[58:61]
	s_waitcnt lgkmcnt(0)
	v_mfma_f32_16x16x32_bf16 v[74:77], v[118:121], v[172:175], v[74:77]
	v_mfma_f32_16x16x32_bf16 v[66:69], v[106:109], v[172:175], v[66:69]
	v_mfma_f32_16x16x32_bf16 v[62:65], v[240:243], v[172:175], v[62:65]
	v_mfma_f32_16x16x32_bf16 v[58:61], v[236:239], v[172:175], v[58:61]
	s_add_i32 s10, s8, 2
	s_cmp_gt_u32 s10, 64
	s_cbranch_scc0 .Lhyb_b1210

; template <int LSEL>
; __device__ __forceinline__ void hy_conv(const bf16_t* Z, const bf16_t* G, f32x4 (&acc)[4][4], int w, int lane) {
;     ...
;     for (int k = 0; k < 4; ++k) {
;       const int js = (q0 + k) * BPT - d;
;       const bool valid = LSEL ? (js >= -1 && js <= NB - 1) : (js >= 0 && js <= NB - 1);
;       if (valid) {
; #pragma unroll
;         for (int mt = 0; mt < 4; ++mt) {
;           acc[k][mt] = __builtin_amdgcn_mfma_f32_16x16x32_bf16(F[3 - mt], bf[k][0], acc[k][mt], 0, 0, 0);
;           acc[k][mt] = __builtin_amdgcn_mfma_f32_16x16x32_bf16(F[5 - mt], bf[k][1], acc[k][mt], 0, 0, 0);
;         }
;       }
;     }
.Lhyb_b1208:
	v_mfma_f32_16x16x32_bf16 v[34:37], v[240:243], v[110:113], v[34:37]
	v_mfma_f32_16x16x32_bf16 v[30:33], v[236:239], v[110:113], v[30:33]
	v_mfma_f32_16x16x32_bf16 v[26:29], v[142:145], v[110:113], v[26:29]
	v_mfma_f32_16x16x32_bf16 v[22:25], v[138:141], v[110:113], v[22:25]
	v_mfma_f32_16x16x32_bf16 v[34:37], v[118:121], v[114:117], v[34:37]
	v_mfma_f32_16x16x32_bf16 v[30:33], v[106:109], v[114:117], v[30:33]
	v_mfma_f32_16x16x32_bf16 v[26:29], v[240:243], v[114:117], v[26:29]
	v_mfma_f32_16x16x32_bf16 v[22:25], v[236:239], v[114:117], v[22:25]
	s_add_i32 s10, s8, 6
	s_cmp_gt_u32 s10, 64
	s_cbranch_scc1 .Lhyb_latch_1205
	s_branch .Lhyb_b1212

; template <int LSEL>
; __device__ __forceinline__ void hy_conv(const bf16_t* Z, const bf16_t* G, f32x4 (&acc)[4][4], int w, int lane) {
;     ...
;     for (int k = 0; k < 4; ++k) {
;       const int js = (q0 + k) * BPT - d;
;       const bool valid = LSEL ? (js >= -1 && js <= NB - 1) : (js >= 0 && js <= NB - 1);
;       if (valid) {
; #pragma unroll
;         for (int mt = 0; mt < 4; ++mt) {
;           acc[k][mt] = __builtin_amdgcn_mfma_f32_16x16x32_bf16(F[3 - mt], bf[k][0], acc[k][mt], 0, 0, 0);
;           acc[k][mt] = __builtin_amdgcn_mfma_f32_16x16x32_bf16(F[5 - mt], bf[k][1], acc[k][mt], 0, 0, 0);
;         }
;       }
;     }
.Lhyb_b1210:
	v_mfma_f32_16x16x32_bf16 v[54:57], v[240:243], v[126:129], v[54:57]
	v_mfma_f32_16x16x32_bf16 v[50:53], v[236:239], v[126:129], v[50:53]
	v_mfma_f32_16x16x32_bf16 v[46:49], v[142:145], v[126:129], v[46:49]
	v_mfma_f32_16x16x32_bf16 v[38:41], v[138:141], v[126:129], v[38:41]
	v_mfma_f32_16x16x32_bf16 v[54:57], v[118:121], v[130:133], v[54:57]
	v_mfma_f32_16x16x32_bf16 v[50:53], v[106:109], v[130:133], v[50:53]
	v_mfma_f32_16x16x32_bf16 v[46:49], v[240:243], v[130:133], v[46:49]
	v_mfma_f32_16x16x32_bf16 v[38:41], v[236:239], v[130:133], v[38:41]
	s_add_i32 s10, s8, 4
	s_cmp_gt_u32 s10, 64
	s_cbranch_scc0 .Lhyb_b1208

; template <int LSEL>
; __device__ __forceinline__ void hy_conv(const bf16_t* Z, const bf16_t* G, f32x4 (&acc)[4][4], int w, int lane) {
;     ...
;     for (int k = 0; k < 4; ++k) {
;       const int js = (q0 + k) * BPT - d;
;       const bool valid = LSEL ? (js >= -1 && js <= NB - 1) : (js >= 0 && js <= NB - 1);
;       if (valid) {
; #pragma unroll
;         for (int mt = 0; mt < 4; ++mt) {
;           acc[k][mt] = __builtin_amdgcn_mfma_f32_16x16x32_bf16(F[3 - mt], bf[k][0], acc[k][mt], 0, 0, 0);
;           acc[k][mt] = __builtin_amdgcn_mfma_f32_16x16x32_bf16(F[5 - mt], bf[k][1], acc[k][mt], 0, 0, 0);
;         }
;       }
;     }
.Lhyb_b1212:
	v_mfma_f32_16x16x32_bf16 v[18:21], v[240:243], v[98:101], v[18:21]
	v_mfma_f32_16x16x32_bf16 v[14:17], v[236:239], v[98:101], v[14:17]
	v_mfma_f32_16x16x32_bf16 v[10:13], v[142:145], v[98:101], v[10:13]
	v_mfma_f32_16x16x32_bf16 v[6:9], v[138:141], v[98:101], v[6:9]
	v_mfma_f32_16x16x32_bf16 v[18:21], v[118:121], v[102:105], v[18:21]
	v_mfma_f32_16x16x32_bf16 v[14:17], v[106:109], v[102:105], v[14:17]
	v_mfma_f32_16x16x32_bf16 v[10:13], v[240:243], v[102:105], v[10:13]
	v_mfma_f32_16x16x32_bf16 v[6:9], v[236:239], v[102:105], v[6:9]
	s_branch .Lhyb_latch_1205
